# fused epilogue pass 2 rewritten by hand: bf16x4 pieces paired across lanes with v_permlane16_swap, 16-byte stores (half the store instructions)
# speedup vs baseline: 1.0304x; 1.0174x over previous
.LBB0_650:
	s_or_b64 exec, exec, s[4:5]
	v_lshl_add_u64 v[130:131], v[148:149], 2, s[34:35]
	s_mov_b64 s[0:1], 0x102000
	v_add_co_u32_e32 v136, vcc, 0x102000, v130
	s_waitcnt lgkmcnt(1)
	v_lshl_add_u64 v[132:133], v[130:131], 0, s[0:1]
	s_mov_b64 s[0:1], 0x104000
	v_addc_co_u32_e32 v137, vcc, 0, v131, vcc
	v_lshl_add_u64 v[134:135], v[130:131], 0, s[0:1]
	v_add_co_u32_e32 v130, vcc, 0x104000, v130
	s_waitcnt lgkmcnt(0)
	s_barrier
	s_nop 0
	v_addc_co_u32_e32 v131, vcc, 0, v131, vcc
	global_load_dwordx4 v[146:149], v[134:135], off offset:64
	global_load_dwordx4 v[150:153], v[132:133], off offset:64
	global_load_dwordx4 v[138:141], v[132:133], off offset:512
	global_load_dwordx4 v[142:145], v[134:135], off offset:512
	global_load_dwordx4 v[154:157], v[136:137], off
	global_load_dwordx4 v[158:161], v[130:131], off
	s_nop 0
	global_load_dwordx4 v[130:133], v[132:133], off offset:576
	s_nop 0
	global_load_dwordx4 v[134:137], v[134:135], off offset:576
	v_or_b32_e32 v224, v185, v183
	s_waitcnt lgkmcnt(0)
	v_or_b32_e32 v225, v187, v224
	v_mov_b32_e32 v248, 0x7fc00000
	v_mov_b32_e32 v249, 0x7fc07fc0
	v_cmp_ne_u32_e32 vcc, 0, v224
	v_cmp_ne_u32_e64 s[0:1], 0, v225
	v_add_u32_e32 v246, v180, v162
	v_lshlrev_b32_e32 v246, 1, v246
	v_and_b32_e32 v247, 16, v0
	v_lshrrev_b32_e32 v247, 1, v247
	v_mad_u32_u24 v246, v247, 3, v246
	s_waitcnt vmcnt(0)
	ds_read_b64 v[244:245], v184 offset:8192
	s_waitcnt lgkmcnt(0)
	v_cndmask_b32_e32 v240, v118, v248, vcc
	v_cndmask_b32_e32 v241, v119, v248, vcc
	v_cndmask_b32_e32 v242, v120, v248, vcc
	v_cndmask_b32_e32 v243, v121, v248, vcc
	v_cvt_pk_bf16_f32 v216, v240, v241
	v_cvt_pk_bf16_f32 v217, v242, v243
	v_pk_mul_f32 v[118:119], v[118:119], v[244:245] op_sel:[0,1]
	v_pk_mul_f32 v[120:121], v[120:121], v[244:245] op_sel:[0,1]
	v_pk_fma_f32 v[118:119], v[154:155], v[118:119], v[158:159]
	v_pk_fma_f32 v[120:121], v[156:157], v[120:121], v[160:161]
	v_cvt_pk_bf16_f32 v232, v118, v119
	v_cvt_pk_bf16_f32 v233, v120, v121
	v_cndmask_b32_e64 v232, v232, v249, s[0:1]
	v_cndmask_b32_e64 v233, v233, v249, s[0:1]
	v_cndmask_b32_e32 v240, v122, v248, vcc
	v_cndmask_b32_e32 v241, v123, v248, vcc
	v_cndmask_b32_e32 v242, v124, v248, vcc
	v_cndmask_b32_e32 v243, v125, v248, vcc
	v_cvt_pk_bf16_f32 v218, v240, v241
	v_cvt_pk_bf16_f32 v219, v242, v243
	v_pk_mul_f32 v[122:123], v[122:123], v[244:245] op_sel:[0,1]
	v_pk_mul_f32 v[124:125], v[124:125], v[244:245] op_sel:[0,1]
	v_pk_fma_f32 v[122:123], v[150:151], v[122:123], v[146:147]
	v_pk_fma_f32 v[124:125], v[152:153], v[124:125], v[148:149]
	v_cvt_pk_bf16_f32 v234, v122, v123
	v_cvt_pk_bf16_f32 v235, v124, v125
	v_cndmask_b32_e64 v234, v234, v249, s[0:1]
	v_cndmask_b32_e64 v235, v235, v249, s[0:1]
	v_permlane16_swap_b32_e32 v216, v218
	v_permlane16_swap_b32_e32 v217, v219
	s_nop 1
	v_permlane16_swap_b32_e32 v232, v234
	v_permlane16_swap_b32_e32 v233, v235
	global_store_dwordx4 v246, v[216:219], s[56:57] sc1
	global_store_dwordx4 v246, v[232:235], s[58:59] sc1
	v_cndmask_b32_e32 v240, v126, v248, vcc
	v_cndmask_b32_e32 v241, v127, v248, vcc
	v_cndmask_b32_e32 v242, v128, v248, vcc
	v_cndmask_b32_e32 v243, v129, v248, vcc
	v_cvt_pk_bf16_f32 v220, v240, v241
	v_cvt_pk_bf16_f32 v221, v242, v243
	v_pk_mul_f32 v[126:127], v[126:127], v[244:245] op_sel:[0,1]
	v_pk_mul_f32 v[128:129], v[128:129], v[244:245] op_sel:[0,1]
	v_pk_fma_f32 v[126:127], v[138:139], v[126:127], v[142:143]
	v_pk_fma_f32 v[128:129], v[140:141], v[128:129], v[144:145]
	v_cvt_pk_bf16_f32 v236, v126, v127
	v_cvt_pk_bf16_f32 v237, v128, v129
	v_cndmask_b32_e64 v236, v236, v249, s[0:1]
	v_cndmask_b32_e64 v237, v237, v249, s[0:1]
	v_cndmask_b32_e32 v240, v114, v248, vcc
	v_cndmask_b32_e32 v241, v115, v248, vcc
	v_cndmask_b32_e32 v242, v116, v248, vcc
	v_cndmask_b32_e32 v243, v117, v248, vcc
	v_cvt_pk_bf16_f32 v222, v240, v241
	v_cvt_pk_bf16_f32 v223, v242, v243
	v_pk_mul_f32 v[114:115], v[114:115], v[244:245] op_sel:[0,1]
	v_pk_mul_f32 v[116:117], v[116:117], v[244:245] op_sel:[0,1]
	v_pk_fma_f32 v[114:115], v[130:131], v[114:115], v[134:135]
	v_pk_fma_f32 v[116:117], v[132:133], v[116:117], v[136:137]
	v_cvt_pk_bf16_f32 v238, v114, v115
	v_cvt_pk_bf16_f32 v239, v116, v117
	v_cndmask_b32_e64 v238, v238, v249, s[0:1]
	v_cndmask_b32_e64 v239, v239, v249, s[0:1]
	v_permlane16_swap_b32_e32 v220, v222
	v_permlane16_swap_b32_e32 v221, v223
	s_nop 1
	v_permlane16_swap_b32_e32 v236, v238
	v_permlane16_swap_b32_e32 v237, v239
	global_store_dwordx4 v246, v[220:223], s[56:57] offset:256 sc1
	global_store_dwordx4 v246, v[236:239], s[58:59] offset:256 sc1
	ds_read_b64 v[244:245], v184 offset:8320
	v_add_u32_e32 v247, 0x8000, v246
	s_waitcnt lgkmcnt(0)
	v_cndmask_b32_e32 v240, v110, v248, vcc
	v_cndmask_b32_e32 v241, v111, v248, vcc
	v_cndmask_b32_e32 v242, v112, v248, vcc
	v_cndmask_b32_e32 v243, v113, v248, vcc
	v_cvt_pk_bf16_f32 v216, v240, v241
	v_cvt_pk_bf16_f32 v217, v242, v243
	v_pk_mul_f32 v[110:111], v[110:111], v[244:245] op_sel:[0,1]
	v_pk_mul_f32 v[112:113], v[112:113], v[244:245] op_sel:[0,1]
	v_pk_fma_f32 v[110:111], v[154:155], v[110:111], v[158:159]
	v_pk_fma_f32 v[112:113], v[156:157], v[112:113], v[160:161]
	v_cvt_pk_bf16_f32 v232, v110, v111
	v_cvt_pk_bf16_f32 v233, v112, v113
	v_cndmask_b32_e64 v232, v232, v249, s[0:1]
	v_cndmask_b32_e64 v233, v233, v249, s[0:1]
	v_cndmask_b32_e32 v240, v106, v248, vcc
	v_cndmask_b32_e32 v241, v107, v248, vcc
	v_cndmask_b32_e32 v242, v108, v248, vcc
	v_cndmask_b32_e32 v243, v109, v248, vcc
	v_cvt_pk_bf16_f32 v218, v240, v241
	v_cvt_pk_bf16_f32 v219, v242, v243
	v_pk_mul_f32 v[106:107], v[106:107], v[244:245] op_sel:[0,1]
	v_pk_mul_f32 v[108:109], v[108:109], v[244:245] op_sel:[0,1]
	v_pk_fma_f32 v[106:107], v[150:151], v[106:107], v[146:147]
	v_pk_fma_f32 v[108:109], v[152:153], v[108:109], v[148:149]
	v_cvt_pk_bf16_f32 v234, v106, v107
	v_cvt_pk_bf16_f32 v235, v108, v109
	v_cndmask_b32_e64 v234, v234, v249, s[0:1]
	v_cndmask_b32_e64 v235, v235, v249, s[0:1]
	v_permlane16_swap_b32_e32 v216, v218
	v_permlane16_swap_b32_e32 v217, v219
	s_nop 1
	v_permlane16_swap_b32_e32 v232, v234
	v_permlane16_swap_b32_e32 v233, v235
	global_store_dwordx4 v247, v[216:219], s[56:57] sc1
	global_store_dwordx4 v247, v[232:235], s[58:59] sc1
	v_cndmask_b32_e32 v240, v102, v248, vcc
	v_cndmask_b32_e32 v241, v103, v248, vcc
	v_cndmask_b32_e32 v242, v104, v248, vcc
	v_cndmask_b32_e32 v243, v105, v248, vcc
	v_cvt_pk_bf16_f32 v220, v240, v241
	v_cvt_pk_bf16_f32 v221, v242, v243
	v_pk_mul_f32 v[102:103], v[102:103], v[244:245] op_sel:[0,1]
	v_pk_mul_f32 v[104:105], v[104:105], v[244:245] op_sel:[0,1]
	v_pk_fma_f32 v[102:103], v[138:139], v[102:103], v[142:143]
	v_pk_fma_f32 v[104:105], v[140:141], v[104:105], v[144:145]
	v_cvt_pk_bf16_f32 v236, v102, v103
	v_cvt_pk_bf16_f32 v237, v104, v105
	v_cndmask_b32_e64 v236, v236, v249, s[0:1]
	v_cndmask_b32_e64 v237, v237, v249, s[0:1]
	v_cndmask_b32_e32 v240, v98, v248, vcc
	v_cndmask_b32_e32 v241, v99, v248, vcc
	v_cndmask_b32_e32 v242, v100, v248, vcc
	v_cndmask_b32_e32 v243, v101, v248, vcc
	v_cvt_pk_bf16_f32 v222, v240, v241
	v_cvt_pk_bf16_f32 v223, v242, v243
	v_pk_mul_f32 v[98:99], v[98:99], v[244:245] op_sel:[0,1]
	v_pk_mul_f32 v[100:101], v[100:101], v[244:245] op_sel:[0,1]
	v_pk_fma_f32 v[98:99], v[130:131], v[98:99], v[134:135]
	v_pk_fma_f32 v[100:101], v[132:133], v[100:101], v[136:137]
	v_cvt_pk_bf16_f32 v238, v98, v99
	v_cvt_pk_bf16_f32 v239, v100, v101
	v_cndmask_b32_e64 v238, v238, v249, s[0:1]
	v_cndmask_b32_e64 v239, v239, v249, s[0:1]
	v_permlane16_swap_b32_e32 v220, v222
	v_permlane16_swap_b32_e32 v221, v223
	s_nop 1
	v_permlane16_swap_b32_e32 v236, v238
	v_permlane16_swap_b32_e32 v237, v239
	global_store_dwordx4 v247, v[220:223], s[56:57] offset:256 sc1
	global_store_dwordx4 v247, v[236:239], s[58:59] offset:256 sc1
	ds_read_b64 v[244:245], v184 offset:8448
	v_add_u32_e32 v247, 0x10000, v246
	s_waitcnt lgkmcnt(0)
	v_cndmask_b32_e32 v240, v94, v248, vcc
	v_cndmask_b32_e32 v241, v95, v248, vcc
	v_cndmask_b32_e32 v242, v96, v248, vcc
	v_cndmask_b32_e32 v243, v97, v248, vcc
	v_cvt_pk_bf16_f32 v216, v240, v241
	v_cvt_pk_bf16_f32 v217, v242, v243
	v_pk_mul_f32 v[94:95], v[94:95], v[244:245] op_sel:[0,1]
	v_pk_mul_f32 v[96:97], v[96:97], v[244:245] op_sel:[0,1]
	v_pk_fma_f32 v[94:95], v[154:155], v[94:95], v[158:159]
	v_pk_fma_f32 v[96:97], v[156:157], v[96:97], v[160:161]
	v_cvt_pk_bf16_f32 v232, v94, v95
	v_cvt_pk_bf16_f32 v233, v96, v97
	v_cndmask_b32_e64 v232, v232, v249, s[0:1]
	v_cndmask_b32_e64 v233, v233, v249, s[0:1]
	v_cndmask_b32_e32 v240, v90, v248, vcc
	v_cndmask_b32_e32 v241, v91, v248, vcc
	v_cndmask_b32_e32 v242, v92, v248, vcc
	v_cndmask_b32_e32 v243, v93, v248, vcc
	v_cvt_pk_bf16_f32 v218, v240, v241
	v_cvt_pk_bf16_f32 v219, v242, v243
	v_pk_mul_f32 v[90:91], v[90:91], v[244:245] op_sel:[0,1]
	v_pk_mul_f32 v[92:93], v[92:93], v[244:245] op_sel:[0,1]
	v_pk_fma_f32 v[90:91], v[150:151], v[90:91], v[146:147]
	v_pk_fma_f32 v[92:93], v[152:153], v[92:93], v[148:149]
	v_cvt_pk_bf16_f32 v234, v90, v91
	v_cvt_pk_bf16_f32 v235, v92, v93
	v_cndmask_b32_e64 v234, v234, v249, s[0:1]
	v_cndmask_b32_e64 v235, v235, v249, s[0:1]
	v_permlane16_swap_b32_e32 v216, v218
	v_permlane16_swap_b32_e32 v217, v219
	s_nop 1
	v_permlane16_swap_b32_e32 v232, v234
	v_permlane16_swap_b32_e32 v233, v235
	global_store_dwordx4 v247, v[216:219], s[56:57] sc1
	global_store_dwordx4 v247, v[232:235], s[58:59] sc1
	v_cndmask_b32_e32 v240, v86, v248, vcc
	v_cndmask_b32_e32 v241, v87, v248, vcc
	v_cndmask_b32_e32 v242, v88, v248, vcc
	v_cndmask_b32_e32 v243, v89, v248, vcc
	v_cvt_pk_bf16_f32 v220, v240, v241
	v_cvt_pk_bf16_f32 v221, v242, v243
	v_pk_mul_f32 v[86:87], v[86:87], v[244:245] op_sel:[0,1]
	v_pk_mul_f32 v[88:89], v[88:89], v[244:245] op_sel:[0,1]
	v_pk_fma_f32 v[86:87], v[138:139], v[86:87], v[142:143]
	v_pk_fma_f32 v[88:89], v[140:141], v[88:89], v[144:145]
	v_cvt_pk_bf16_f32 v236, v86, v87
	v_cvt_pk_bf16_f32 v237, v88, v89
	v_cndmask_b32_e64 v236, v236, v249, s[0:1]
	v_cndmask_b32_e64 v237, v237, v249, s[0:1]
	v_cndmask_b32_e32 v240, v82, v248, vcc
	v_cndmask_b32_e32 v241, v83, v248, vcc
	v_cndmask_b32_e32 v242, v84, v248, vcc
	v_cndmask_b32_e32 v243, v85, v248, vcc
	v_cvt_pk_bf16_f32 v222, v240, v241
	v_cvt_pk_bf16_f32 v223, v242, v243
	v_pk_mul_f32 v[82:83], v[82:83], v[244:245] op_sel:[0,1]
	v_pk_mul_f32 v[84:85], v[84:85], v[244:245] op_sel:[0,1]
	v_pk_fma_f32 v[82:83], v[130:131], v[82:83], v[134:135]
	v_pk_fma_f32 v[84:85], v[132:133], v[84:85], v[136:137]
	v_cvt_pk_bf16_f32 v238, v82, v83
	v_cvt_pk_bf16_f32 v239, v84, v85
	v_cndmask_b32_e64 v238, v238, v249, s[0:1]
	v_cndmask_b32_e64 v239, v239, v249, s[0:1]
	v_permlane16_swap_b32_e32 v220, v222
	v_permlane16_swap_b32_e32 v221, v223
	s_nop 1
	v_permlane16_swap_b32_e32 v236, v238
	v_permlane16_swap_b32_e32 v237, v239
	global_store_dwordx4 v247, v[220:223], s[56:57] offset:256 sc1
	global_store_dwordx4 v247, v[236:239], s[58:59] offset:256 sc1
	ds_read_b64 v[244:245], v184 offset:8576
	v_add_u32_e32 v247, 0x18000, v246
	s_waitcnt lgkmcnt(0)
	v_cndmask_b32_e32 v240, v78, v248, vcc
	v_cndmask_b32_e32 v241, v79, v248, vcc
	v_cndmask_b32_e32 v242, v80, v248, vcc
	v_cndmask_b32_e32 v243, v81, v248, vcc
	v_cvt_pk_bf16_f32 v216, v240, v241
	v_cvt_pk_bf16_f32 v217, v242, v243
	v_pk_mul_f32 v[78:79], v[78:79], v[244:245] op_sel:[0,1]
	v_pk_mul_f32 v[80:81], v[80:81], v[244:245] op_sel:[0,1]
	v_pk_fma_f32 v[78:79], v[154:155], v[78:79], v[158:159]
	v_pk_fma_f32 v[80:81], v[156:157], v[80:81], v[160:161]
	v_cvt_pk_bf16_f32 v232, v78, v79
	v_cvt_pk_bf16_f32 v233, v80, v81
	v_cndmask_b32_e64 v232, v232, v249, s[0:1]
	v_cndmask_b32_e64 v233, v233, v249, s[0:1]
	v_cndmask_b32_e32 v240, v74, v248, vcc
	v_cndmask_b32_e32 v241, v75, v248, vcc
	v_cndmask_b32_e32 v242, v76, v248, vcc
	v_cndmask_b32_e32 v243, v77, v248, vcc
	v_cvt_pk_bf16_f32 v218, v240, v241
	v_cvt_pk_bf16_f32 v219, v242, v243
	v_pk_mul_f32 v[74:75], v[74:75], v[244:245] op_sel:[0,1]
	v_pk_mul_f32 v[76:77], v[76:77], v[244:245] op_sel:[0,1]
	v_pk_fma_f32 v[74:75], v[150:151], v[74:75], v[146:147]
	v_pk_fma_f32 v[76:77], v[152:153], v[76:77], v[148:149]
	v_cvt_pk_bf16_f32 v234, v74, v75
	v_cvt_pk_bf16_f32 v235, v76, v77
	v_cndmask_b32_e64 v234, v234, v249, s[0:1]
	v_cndmask_b32_e64 v235, v235, v249, s[0:1]
	v_permlane16_swap_b32_e32 v216, v218
	v_permlane16_swap_b32_e32 v217, v219
	s_nop 1
	v_permlane16_swap_b32_e32 v232, v234
	v_permlane16_swap_b32_e32 v233, v235
	global_store_dwordx4 v247, v[216:219], s[56:57] sc1
	global_store_dwordx4 v247, v[232:235], s[58:59] sc1
	v_cndmask_b32_e32 v240, v70, v248, vcc
	v_cndmask_b32_e32 v241, v71, v248, vcc
	v_cndmask_b32_e32 v242, v72, v248, vcc
	v_cndmask_b32_e32 v243, v73, v248, vcc
	v_cvt_pk_bf16_f32 v220, v240, v241
	v_cvt_pk_bf16_f32 v221, v242, v243
	v_pk_mul_f32 v[70:71], v[70:71], v[244:245] op_sel:[0,1]
	v_pk_mul_f32 v[72:73], v[72:73], v[244:245] op_sel:[0,1]
	v_pk_fma_f32 v[70:71], v[138:139], v[70:71], v[142:143]
	v_pk_fma_f32 v[72:73], v[140:141], v[72:73], v[144:145]
	v_cvt_pk_bf16_f32 v236, v70, v71
	v_cvt_pk_bf16_f32 v237, v72, v73
	v_cndmask_b32_e64 v236, v236, v249, s[0:1]
	v_cndmask_b32_e64 v237, v237, v249, s[0:1]
	v_cndmask_b32_e32 v240, v66, v248, vcc
	v_cndmask_b32_e32 v241, v67, v248, vcc
	v_cndmask_b32_e32 v242, v68, v248, vcc
	v_cndmask_b32_e32 v243, v69, v248, vcc
	v_cvt_pk_bf16_f32 v222, v240, v241
	v_cvt_pk_bf16_f32 v223, v242, v243
	v_pk_mul_f32 v[66:67], v[66:67], v[244:245] op_sel:[0,1]
	v_pk_mul_f32 v[68:69], v[68:69], v[244:245] op_sel:[0,1]
	v_pk_fma_f32 v[66:67], v[130:131], v[66:67], v[134:135]
	v_pk_fma_f32 v[68:69], v[132:133], v[68:69], v[136:137]
	v_cvt_pk_bf16_f32 v238, v66, v67
	v_cvt_pk_bf16_f32 v239, v68, v69
	v_cndmask_b32_e64 v238, v238, v249, s[0:1]
	v_cndmask_b32_e64 v239, v239, v249, s[0:1]
	v_permlane16_swap_b32_e32 v220, v222
	v_permlane16_swap_b32_e32 v221, v223
	s_nop 1
	v_permlane16_swap_b32_e32 v236, v238
	v_permlane16_swap_b32_e32 v237, v239
	global_store_dwordx4 v247, v[220:223], s[56:57] offset:256 sc1
	global_store_dwordx4 v247, v[236:239], s[58:59] offset:256 sc1
	ds_read_b64 v[244:245], v184 offset:9216
	v_add_u32_e32 v247, 0x40000, v246
	s_waitcnt lgkmcnt(0)
	v_cndmask_b32_e32 v240, v62, v248, vcc
	v_cndmask_b32_e32 v241, v63, v248, vcc
	v_cndmask_b32_e32 v242, v64, v248, vcc
	v_cndmask_b32_e32 v243, v65, v248, vcc
	v_cvt_pk_bf16_f32 v216, v240, v241
	v_cvt_pk_bf16_f32 v217, v242, v243
	v_pk_mul_f32 v[62:63], v[62:63], v[244:245] op_sel:[0,1]
	v_pk_mul_f32 v[64:65], v[64:65], v[244:245] op_sel:[0,1]
	v_pk_fma_f32 v[62:63], v[154:155], v[62:63], v[158:159]
	v_pk_fma_f32 v[64:65], v[156:157], v[64:65], v[160:161]
	v_cvt_pk_bf16_f32 v232, v62, v63
	v_cvt_pk_bf16_f32 v233, v64, v65
	v_cndmask_b32_e64 v232, v232, v249, s[0:1]
	v_cndmask_b32_e64 v233, v233, v249, s[0:1]
	v_cndmask_b32_e32 v240, v58, v248, vcc
	v_cndmask_b32_e32 v241, v59, v248, vcc
	v_cndmask_b32_e32 v242, v60, v248, vcc
	v_cndmask_b32_e32 v243, v61, v248, vcc
	v_cvt_pk_bf16_f32 v218, v240, v241
	v_cvt_pk_bf16_f32 v219, v242, v243
	v_pk_mul_f32 v[58:59], v[58:59], v[244:245] op_sel:[0,1]
	v_pk_mul_f32 v[60:61], v[60:61], v[244:245] op_sel:[0,1]
	v_pk_fma_f32 v[58:59], v[150:151], v[58:59], v[146:147]
	v_pk_fma_f32 v[60:61], v[152:153], v[60:61], v[148:149]
	v_cvt_pk_bf16_f32 v234, v58, v59
	v_cvt_pk_bf16_f32 v235, v60, v61
	v_cndmask_b32_e64 v234, v234, v249, s[0:1]
	v_cndmask_b32_e64 v235, v235, v249, s[0:1]
	v_permlane16_swap_b32_e32 v216, v218
	v_permlane16_swap_b32_e32 v217, v219
	s_nop 1
	v_permlane16_swap_b32_e32 v232, v234
	v_permlane16_swap_b32_e32 v233, v235
	global_store_dwordx4 v247, v[216:219], s[56:57] sc1
	global_store_dwordx4 v247, v[232:235], s[58:59] sc1
	v_cndmask_b32_e32 v240, v54, v248, vcc
	v_cndmask_b32_e32 v241, v55, v248, vcc
	v_cndmask_b32_e32 v242, v56, v248, vcc
	v_cndmask_b32_e32 v243, v57, v248, vcc
	v_cvt_pk_bf16_f32 v220, v240, v241
	v_cvt_pk_bf16_f32 v221, v242, v243
	v_pk_mul_f32 v[54:55], v[54:55], v[244:245] op_sel:[0,1]
	v_pk_mul_f32 v[56:57], v[56:57], v[244:245] op_sel:[0,1]
	v_pk_fma_f32 v[54:55], v[138:139], v[54:55], v[142:143]
	v_pk_fma_f32 v[56:57], v[140:141], v[56:57], v[144:145]
	v_cvt_pk_bf16_f32 v236, v54, v55
	v_cvt_pk_bf16_f32 v237, v56, v57
	v_cndmask_b32_e64 v236, v236, v249, s[0:1]
	v_cndmask_b32_e64 v237, v237, v249, s[0:1]
	v_cndmask_b32_e32 v240, v50, v248, vcc
	v_cndmask_b32_e32 v241, v51, v248, vcc
	v_cndmask_b32_e32 v242, v52, v248, vcc
	v_cndmask_b32_e32 v243, v53, v248, vcc
	v_cvt_pk_bf16_f32 v222, v240, v241
	v_cvt_pk_bf16_f32 v223, v242, v243
	v_pk_mul_f32 v[50:51], v[50:51], v[244:245] op_sel:[0,1]
	v_pk_mul_f32 v[52:53], v[52:53], v[244:245] op_sel:[0,1]
	v_pk_fma_f32 v[50:51], v[130:131], v[50:51], v[134:135]
	v_pk_fma_f32 v[52:53], v[132:133], v[52:53], v[136:137]
	v_cvt_pk_bf16_f32 v238, v50, v51
	v_cvt_pk_bf16_f32 v239, v52, v53
	v_cndmask_b32_e64 v238, v238, v249, s[0:1]
	v_cndmask_b32_e64 v239, v239, v249, s[0:1]
	v_permlane16_swap_b32_e32 v220, v222
	v_permlane16_swap_b32_e32 v221, v223
	s_nop 1
	v_permlane16_swap_b32_e32 v236, v238
	v_permlane16_swap_b32_e32 v237, v239
	global_store_dwordx4 v247, v[220:223], s[56:57] offset:256 sc1
	global_store_dwordx4 v247, v[236:239], s[58:59] offset:256 sc1
	ds_read_b64 v[244:245], v184 offset:9344
	v_add_u32_e32 v247, 0x48000, v246
	s_waitcnt lgkmcnt(0)
	v_cndmask_b32_e32 v240, v46, v248, vcc
	v_cndmask_b32_e32 v241, v47, v248, vcc
	v_cndmask_b32_e32 v242, v48, v248, vcc
	v_cndmask_b32_e32 v243, v49, v248, vcc
	v_cvt_pk_bf16_f32 v216, v240, v241
	v_cvt_pk_bf16_f32 v217, v242, v243
	v_pk_mul_f32 v[46:47], v[46:47], v[244:245] op_sel:[0,1]
	v_pk_mul_f32 v[48:49], v[48:49], v[244:245] op_sel:[0,1]
	v_pk_fma_f32 v[46:47], v[154:155], v[46:47], v[158:159]
	v_pk_fma_f32 v[48:49], v[156:157], v[48:49], v[160:161]
	v_cvt_pk_bf16_f32 v232, v46, v47
	v_cvt_pk_bf16_f32 v233, v48, v49
	v_cndmask_b32_e64 v232, v232, v249, s[0:1]
	v_cndmask_b32_e64 v233, v233, v249, s[0:1]
	v_cndmask_b32_e32 v240, v42, v248, vcc
	v_cndmask_b32_e32 v241, v43, v248, vcc
	v_cndmask_b32_e32 v242, v44, v248, vcc
	v_cndmask_b32_e32 v243, v45, v248, vcc
	v_cvt_pk_bf16_f32 v218, v240, v241
	v_cvt_pk_bf16_f32 v219, v242, v243
	v_pk_mul_f32 v[42:43], v[42:43], v[244:245] op_sel:[0,1]
	v_pk_mul_f32 v[44:45], v[44:45], v[244:245] op_sel:[0,1]
	v_pk_fma_f32 v[42:43], v[150:151], v[42:43], v[146:147]
	v_pk_fma_f32 v[44:45], v[152:153], v[44:45], v[148:149]
	v_cvt_pk_bf16_f32 v234, v42, v43
	v_cvt_pk_bf16_f32 v235, v44, v45
	v_cndmask_b32_e64 v234, v234, v249, s[0:1]
	v_cndmask_b32_e64 v235, v235, v249, s[0:1]
	v_permlane16_swap_b32_e32 v216, v218
	v_permlane16_swap_b32_e32 v217, v219
	s_nop 1
	v_permlane16_swap_b32_e32 v232, v234
	v_permlane16_swap_b32_e32 v233, v235
	global_store_dwordx4 v247, v[216:219], s[56:57] sc1
	global_store_dwordx4 v247, v[232:235], s[58:59] sc1
	v_cndmask_b32_e32 v240, v38, v248, vcc
	v_cndmask_b32_e32 v241, v39, v248, vcc
	v_cndmask_b32_e32 v242, v40, v248, vcc
	v_cndmask_b32_e32 v243, v41, v248, vcc
	v_cvt_pk_bf16_f32 v220, v240, v241
	v_cvt_pk_bf16_f32 v221, v242, v243
	v_pk_mul_f32 v[38:39], v[38:39], v[244:245] op_sel:[0,1]
	v_pk_mul_f32 v[40:41], v[40:41], v[244:245] op_sel:[0,1]
	v_pk_fma_f32 v[38:39], v[138:139], v[38:39], v[142:143]
	v_pk_fma_f32 v[40:41], v[140:141], v[40:41], v[144:145]
	v_cvt_pk_bf16_f32 v236, v38, v39
	v_cvt_pk_bf16_f32 v237, v40, v41
	v_cndmask_b32_e64 v236, v236, v249, s[0:1]
	v_cndmask_b32_e64 v237, v237, v249, s[0:1]
	v_cndmask_b32_e32 v240, v34, v248, vcc
	v_cndmask_b32_e32 v241, v35, v248, vcc
	v_cndmask_b32_e32 v242, v36, v248, vcc
	v_cndmask_b32_e32 v243, v37, v248, vcc
	v_cvt_pk_bf16_f32 v222, v240, v241
	v_cvt_pk_bf16_f32 v223, v242, v243
	v_pk_mul_f32 v[34:35], v[34:35], v[244:245] op_sel:[0,1]
	v_pk_mul_f32 v[36:37], v[36:37], v[244:245] op_sel:[0,1]
	v_pk_fma_f32 v[34:35], v[130:131], v[34:35], v[134:135]
	v_pk_fma_f32 v[36:37], v[132:133], v[36:37], v[136:137]
	v_cvt_pk_bf16_f32 v238, v34, v35
	v_cvt_pk_bf16_f32 v239, v36, v37
	v_cndmask_b32_e64 v238, v238, v249, s[0:1]
	v_cndmask_b32_e64 v239, v239, v249, s[0:1]
	v_permlane16_swap_b32_e32 v220, v222
	v_permlane16_swap_b32_e32 v221, v223
	s_nop 1
	v_permlane16_swap_b32_e32 v236, v238
	v_permlane16_swap_b32_e32 v237, v239
	global_store_dwordx4 v247, v[220:223], s[56:57] offset:256 sc1
	global_store_dwordx4 v247, v[236:239], s[58:59] offset:256 sc1
	ds_read_b64 v[244:245], v184 offset:9472
	v_add_u32_e32 v247, 0x50000, v246
	s_waitcnt lgkmcnt(0)
	v_cndmask_b32_e32 v240, v30, v248, vcc
	v_cndmask_b32_e32 v241, v31, v248, vcc
	v_cndmask_b32_e32 v242, v32, v248, vcc
	v_cndmask_b32_e32 v243, v33, v248, vcc
	v_cvt_pk_bf16_f32 v216, v240, v241
	v_cvt_pk_bf16_f32 v217, v242, v243
	v_pk_mul_f32 v[30:31], v[30:31], v[244:245] op_sel:[0,1]
	v_pk_mul_f32 v[32:33], v[32:33], v[244:245] op_sel:[0,1]
	v_pk_fma_f32 v[30:31], v[154:155], v[30:31], v[158:159]
	v_pk_fma_f32 v[32:33], v[156:157], v[32:33], v[160:161]
	v_cvt_pk_bf16_f32 v232, v30, v31
	v_cvt_pk_bf16_f32 v233, v32, v33
	v_cndmask_b32_e64 v232, v232, v249, s[0:1]
	v_cndmask_b32_e64 v233, v233, v249, s[0:1]
	v_cndmask_b32_e32 v240, v26, v248, vcc
	v_cndmask_b32_e32 v241, v27, v248, vcc
	v_cndmask_b32_e32 v242, v28, v248, vcc
	v_cndmask_b32_e32 v243, v29, v248, vcc
	v_cvt_pk_bf16_f32 v218, v240, v241
	v_cvt_pk_bf16_f32 v219, v242, v243
	v_pk_mul_f32 v[26:27], v[26:27], v[244:245] op_sel:[0,1]
	v_pk_mul_f32 v[28:29], v[28:29], v[244:245] op_sel:[0,1]
	v_pk_fma_f32 v[26:27], v[150:151], v[26:27], v[146:147]
	v_pk_fma_f32 v[28:29], v[152:153], v[28:29], v[148:149]
	v_cvt_pk_bf16_f32 v234, v26, v27
	v_cvt_pk_bf16_f32 v235, v28, v29
	v_cndmask_b32_e64 v234, v234, v249, s[0:1]
	v_cndmask_b32_e64 v235, v235, v249, s[0:1]
	v_permlane16_swap_b32_e32 v216, v218
	v_permlane16_swap_b32_e32 v217, v219
	s_nop 1
	v_permlane16_swap_b32_e32 v232, v234
	v_permlane16_swap_b32_e32 v233, v235
	global_store_dwordx4 v247, v[216:219], s[56:57] sc1
	global_store_dwordx4 v247, v[232:235], s[58:59] sc1
	v_cndmask_b32_e32 v240, v22, v248, vcc
	v_cndmask_b32_e32 v241, v23, v248, vcc
	v_cndmask_b32_e32 v242, v24, v248, vcc
	v_cndmask_b32_e32 v243, v25, v248, vcc
	v_cvt_pk_bf16_f32 v220, v240, v241
	v_cvt_pk_bf16_f32 v221, v242, v243
	v_pk_mul_f32 v[22:23], v[22:23], v[244:245] op_sel:[0,1]
	v_pk_mul_f32 v[24:25], v[24:25], v[244:245] op_sel:[0,1]
	v_pk_fma_f32 v[22:23], v[138:139], v[22:23], v[142:143]
	v_pk_fma_f32 v[24:25], v[140:141], v[24:25], v[144:145]
	v_cvt_pk_bf16_f32 v236, v22, v23
	v_cvt_pk_bf16_f32 v237, v24, v25
	v_cndmask_b32_e64 v236, v236, v249, s[0:1]
	v_cndmask_b32_e64 v237, v237, v249, s[0:1]
	v_cndmask_b32_e32 v240, v18, v248, vcc
	v_cndmask_b32_e32 v241, v19, v248, vcc
	v_cndmask_b32_e32 v242, v20, v248, vcc
	v_cndmask_b32_e32 v243, v21, v248, vcc
	v_cvt_pk_bf16_f32 v222, v240, v241
	v_cvt_pk_bf16_f32 v223, v242, v243
	v_pk_mul_f32 v[18:19], v[18:19], v[244:245] op_sel:[0,1]
	v_pk_mul_f32 v[20:21], v[20:21], v[244:245] op_sel:[0,1]
	v_pk_fma_f32 v[18:19], v[130:131], v[18:19], v[134:135]
	v_pk_fma_f32 v[20:21], v[132:133], v[20:21], v[136:137]
	v_cvt_pk_bf16_f32 v238, v18, v19
	v_cvt_pk_bf16_f32 v239, v20, v21
	v_cndmask_b32_e64 v238, v238, v249, s[0:1]
	v_cndmask_b32_e64 v239, v239, v249, s[0:1]
	v_permlane16_swap_b32_e32 v220, v222
	v_permlane16_swap_b32_e32 v221, v223
	s_nop 1
	v_permlane16_swap_b32_e32 v236, v238
	v_permlane16_swap_b32_e32 v237, v239
	global_store_dwordx4 v247, v[220:223], s[56:57] offset:256 sc1
	global_store_dwordx4 v247, v[236:239], s[58:59] offset:256 sc1
	ds_read_b64 v[244:245], v184 offset:9600
	v_add_u32_e32 v247, 0x58000, v246
	s_waitcnt lgkmcnt(0)
	v_cndmask_b32_e32 v240, v14, v248, vcc
	v_cndmask_b32_e32 v241, v15, v248, vcc
	v_cndmask_b32_e32 v242, v16, v248, vcc
	v_cndmask_b32_e32 v243, v17, v248, vcc
	v_cvt_pk_bf16_f32 v216, v240, v241
	v_cvt_pk_bf16_f32 v217, v242, v243
	v_pk_mul_f32 v[14:15], v[14:15], v[244:245] op_sel:[0,1]
	v_pk_mul_f32 v[16:17], v[16:17], v[244:245] op_sel:[0,1]
	v_pk_fma_f32 v[14:15], v[154:155], v[14:15], v[158:159]
	v_pk_fma_f32 v[16:17], v[156:157], v[16:17], v[160:161]
	v_cvt_pk_bf16_f32 v232, v14, v15
	v_cvt_pk_bf16_f32 v233, v16, v17
	v_cndmask_b32_e64 v232, v232, v249, s[0:1]
	v_cndmask_b32_e64 v233, v233, v249, s[0:1]
	v_cndmask_b32_e32 v240, v10, v248, vcc
	v_cndmask_b32_e32 v241, v11, v248, vcc
	v_cndmask_b32_e32 v242, v12, v248, vcc
	v_cndmask_b32_e32 v243, v13, v248, vcc
	v_cvt_pk_bf16_f32 v218, v240, v241
	v_cvt_pk_bf16_f32 v219, v242, v243
	v_pk_mul_f32 v[10:11], v[10:11], v[244:245] op_sel:[0,1]
	v_pk_mul_f32 v[12:13], v[12:13], v[244:245] op_sel:[0,1]
	v_pk_fma_f32 v[10:11], v[150:151], v[10:11], v[146:147]
	v_pk_fma_f32 v[12:13], v[152:153], v[12:13], v[148:149]
	v_cvt_pk_bf16_f32 v234, v10, v11
	v_cvt_pk_bf16_f32 v235, v12, v13
	v_cndmask_b32_e64 v234, v234, v249, s[0:1]
	v_cndmask_b32_e64 v235, v235, v249, s[0:1]
	v_permlane16_swap_b32_e32 v216, v218
	v_permlane16_swap_b32_e32 v217, v219
	s_nop 1
	v_permlane16_swap_b32_e32 v232, v234
	v_permlane16_swap_b32_e32 v233, v235
	global_store_dwordx4 v247, v[216:219], s[56:57] sc1
	global_store_dwordx4 v247, v[232:235], s[58:59] sc1
	v_cndmask_b32_e32 v240, v6, v248, vcc
	v_cndmask_b32_e32 v241, v7, v248, vcc
	v_cndmask_b32_e32 v242, v8, v248, vcc
	v_cndmask_b32_e32 v243, v9, v248, vcc
	v_cvt_pk_bf16_f32 v220, v240, v241
	v_cvt_pk_bf16_f32 v221, v242, v243
	v_pk_mul_f32 v[6:7], v[6:7], v[244:245] op_sel:[0,1]
	v_pk_mul_f32 v[8:9], v[8:9], v[244:245] op_sel:[0,1]
	v_pk_fma_f32 v[6:7], v[138:139], v[6:7], v[142:143]
	v_pk_fma_f32 v[8:9], v[140:141], v[8:9], v[144:145]
	v_cvt_pk_bf16_f32 v236, v6, v7
	v_cvt_pk_bf16_f32 v237, v8, v9
	v_cndmask_b32_e64 v236, v236, v249, s[0:1]
	v_cndmask_b32_e64 v237, v237, v249, s[0:1]
	v_cndmask_b32_e32 v240, v2, v248, vcc
	v_cndmask_b32_e32 v241, v3, v248, vcc
	v_cndmask_b32_e32 v242, v4, v248, vcc
	v_cndmask_b32_e32 v243, v5, v248, vcc
	v_cvt_pk_bf16_f32 v222, v240, v241
	v_cvt_pk_bf16_f32 v223, v242, v243
	v_pk_mul_f32 v[2:3], v[2:3], v[244:245] op_sel:[0,1]
	v_pk_mul_f32 v[4:5], v[4:5], v[244:245] op_sel:[0,1]
	v_pk_fma_f32 v[2:3], v[130:131], v[2:3], v[134:135]
	v_pk_fma_f32 v[4:5], v[132:133], v[4:5], v[136:137]
	v_cvt_pk_bf16_f32 v238, v2, v3
	v_cvt_pk_bf16_f32 v239, v4, v5
	v_cndmask_b32_e64 v238, v238, v249, s[0:1]
	v_cndmask_b32_e64 v239, v239, v249, s[0:1]
	v_permlane16_swap_b32_e32 v220, v222
	v_permlane16_swap_b32_e32 v221, v223
	s_nop 1
	v_permlane16_swap_b32_e32 v236, v238
	v_permlane16_swap_b32_e32 v237, v239
	global_store_dwordx4 v247, v[220:223], s[56:57] offset:256 sc1
	global_store_dwordx4 v247, v[236:239], s[58:59] offset:256 sc1

.LBB0_936:
	s_or_b64 exec, exec, s[6:7]
	s_waitcnt lgkmcnt(1)
	v_add_co_u32_e32 v132, vcc, 0x108000, v148
	s_mov_b64 s[0:1], 0x108000
	s_nop 0
	v_addc_co_u32_e32 v133, vcc, 0, v149, vcc
	v_lshl_add_u64 v[130:131], v[148:149], 0, s[0:1]
	s_mov_b64 s[0:1], 0x10a000
	v_add_co_u32_e32 v136, vcc, 0x10a000, v148
	s_waitcnt lgkmcnt(0)
	s_barrier
	v_lshl_add_u64 v[134:135], v[148:149], 0, s[0:1]
	v_addc_co_u32_e32 v137, vcc, 0, v149, vcc
	global_load_dwordx4 v[146:149], v[134:135], off offset:64
	global_load_dwordx4 v[150:153], v[130:131], off offset:64
	global_load_dwordx4 v[138:141], v[130:131], off offset:512
	global_load_dwordx4 v[142:145], v[134:135], off offset:512
	global_load_dwordx4 v[154:157], v[132:133], off
	global_load_dwordx4 v[158:161], v[136:137], off
	s_nop 0
	global_load_dwordx4 v[130:133], v[130:131], off offset:576
	s_nop 0
	global_load_dwordx4 v[134:137], v[134:135], off offset:576
	v_or_b32_e32 v224, v186, v184
	s_waitcnt lgkmcnt(0)
	v_or_b32_e32 v225, v188, v224
	v_mov_b32_e32 v248, 0x7fc00000
	v_mov_b32_e32 v249, 0x7fc07fc0
	v_cmp_ne_u32_e32 vcc, 0, v224
	v_cmp_ne_u32_e64 s[0:1], 0, v225
	v_add_u32_e32 v246, v180, v162
	v_lshlrev_b32_e32 v246, 1, v246
	v_and_b32_e32 v247, 16, v0
	v_lshrrev_b32_e32 v247, 1, v247
	v_mad_u32_u24 v246, v247, 3, v246
	s_waitcnt vmcnt(0)
	ds_read_b64 v[244:245], v185 offset:8192
	s_waitcnt lgkmcnt(0)
	v_cndmask_b32_e32 v240, v118, v248, vcc
	v_cndmask_b32_e32 v241, v119, v248, vcc
	v_cndmask_b32_e32 v242, v120, v248, vcc
	v_cndmask_b32_e32 v243, v121, v248, vcc
	v_cvt_pk_bf16_f32 v216, v240, v241
	v_cvt_pk_bf16_f32 v217, v242, v243
	v_pk_mul_f32 v[118:119], v[118:119], v[244:245] op_sel:[0,1]
	v_pk_mul_f32 v[120:121], v[120:121], v[244:245] op_sel:[0,1]
	v_pk_fma_f32 v[118:119], v[154:155], v[118:119], v[158:159]
	v_pk_fma_f32 v[120:121], v[156:157], v[120:121], v[160:161]
	v_cvt_pk_bf16_f32 v232, v118, v119
	v_cvt_pk_bf16_f32 v233, v120, v121
	v_cndmask_b32_e64 v232, v232, v249, s[0:1]
	v_cndmask_b32_e64 v233, v233, v249, s[0:1]
	v_cndmask_b32_e32 v240, v122, v248, vcc
	v_cndmask_b32_e32 v241, v123, v248, vcc
	v_cndmask_b32_e32 v242, v124, v248, vcc
	v_cndmask_b32_e32 v243, v125, v248, vcc
	v_cvt_pk_bf16_f32 v218, v240, v241
	v_cvt_pk_bf16_f32 v219, v242, v243
	v_pk_mul_f32 v[122:123], v[122:123], v[244:245] op_sel:[0,1]
	v_pk_mul_f32 v[124:125], v[124:125], v[244:245] op_sel:[0,1]
	v_pk_fma_f32 v[122:123], v[150:151], v[122:123], v[146:147]
	v_pk_fma_f32 v[124:125], v[152:153], v[124:125], v[148:149]
	v_cvt_pk_bf16_f32 v234, v122, v123
	v_cvt_pk_bf16_f32 v235, v124, v125
	v_cndmask_b32_e64 v234, v234, v249, s[0:1]
	v_cndmask_b32_e64 v235, v235, v249, s[0:1]
	v_permlane16_swap_b32_e32 v216, v218
	v_permlane16_swap_b32_e32 v217, v219
	s_nop 1
	v_permlane16_swap_b32_e32 v232, v234
	v_permlane16_swap_b32_e32 v233, v235
	global_store_dwordx4 v246, v[216:219], s[94:95] sc1
	global_store_dwordx4 v246, v[232:235], s[58:59] sc1
	v_cndmask_b32_e32 v240, v126, v248, vcc
	v_cndmask_b32_e32 v241, v127, v248, vcc
	v_cndmask_b32_e32 v242, v128, v248, vcc
	v_cndmask_b32_e32 v243, v129, v248, vcc
	v_cvt_pk_bf16_f32 v220, v240, v241
	v_cvt_pk_bf16_f32 v221, v242, v243
	v_pk_mul_f32 v[126:127], v[126:127], v[244:245] op_sel:[0,1]
	v_pk_mul_f32 v[128:129], v[128:129], v[244:245] op_sel:[0,1]
	v_pk_fma_f32 v[126:127], v[138:139], v[126:127], v[142:143]
	v_pk_fma_f32 v[128:129], v[140:141], v[128:129], v[144:145]
	v_cvt_pk_bf16_f32 v236, v126, v127
	v_cvt_pk_bf16_f32 v237, v128, v129
	v_cndmask_b32_e64 v236, v236, v249, s[0:1]
	v_cndmask_b32_e64 v237, v237, v249, s[0:1]
	v_cndmask_b32_e32 v240, v114, v248, vcc
	v_cndmask_b32_e32 v241, v115, v248, vcc
	v_cndmask_b32_e32 v242, v116, v248, vcc
	v_cndmask_b32_e32 v243, v117, v248, vcc
	v_cvt_pk_bf16_f32 v222, v240, v241
	v_cvt_pk_bf16_f32 v223, v242, v243
	v_pk_mul_f32 v[114:115], v[114:115], v[244:245] op_sel:[0,1]
	v_pk_mul_f32 v[116:117], v[116:117], v[244:245] op_sel:[0,1]
	v_pk_fma_f32 v[114:115], v[130:131], v[114:115], v[134:135]
	v_pk_fma_f32 v[116:117], v[132:133], v[116:117], v[136:137]
	v_cvt_pk_bf16_f32 v238, v114, v115
	v_cvt_pk_bf16_f32 v239, v116, v117
	v_cndmask_b32_e64 v238, v238, v249, s[0:1]
	v_cndmask_b32_e64 v239, v239, v249, s[0:1]
	v_permlane16_swap_b32_e32 v220, v222
	v_permlane16_swap_b32_e32 v221, v223
	s_nop 1
	v_permlane16_swap_b32_e32 v236, v238
	v_permlane16_swap_b32_e32 v237, v239
	global_store_dwordx4 v246, v[220:223], s[94:95] offset:256 sc1
	global_store_dwordx4 v246, v[236:239], s[58:59] offset:256 sc1
	ds_read_b64 v[244:245], v185 offset:8320
	v_add_u32_e32 v247, 0x8000, v246
	s_waitcnt lgkmcnt(0)
	v_cndmask_b32_e32 v240, v110, v248, vcc
	v_cndmask_b32_e32 v241, v111, v248, vcc
	v_cndmask_b32_e32 v242, v112, v248, vcc
	v_cndmask_b32_e32 v243, v113, v248, vcc
	v_cvt_pk_bf16_f32 v216, v240, v241
	v_cvt_pk_bf16_f32 v217, v242, v243
	v_pk_mul_f32 v[110:111], v[110:111], v[244:245] op_sel:[0,1]
	v_pk_mul_f32 v[112:113], v[112:113], v[244:245] op_sel:[0,1]
	v_pk_fma_f32 v[110:111], v[154:155], v[110:111], v[158:159]
	v_pk_fma_f32 v[112:113], v[156:157], v[112:113], v[160:161]
	v_cvt_pk_bf16_f32 v232, v110, v111
	v_cvt_pk_bf16_f32 v233, v112, v113
	v_cndmask_b32_e64 v232, v232, v249, s[0:1]
	v_cndmask_b32_e64 v233, v233, v249, s[0:1]
	v_cndmask_b32_e32 v240, v106, v248, vcc
	v_cndmask_b32_e32 v241, v107, v248, vcc
	v_cndmask_b32_e32 v242, v108, v248, vcc
	v_cndmask_b32_e32 v243, v109, v248, vcc
	v_cvt_pk_bf16_f32 v218, v240, v241
	v_cvt_pk_bf16_f32 v219, v242, v243
	v_pk_mul_f32 v[106:107], v[106:107], v[244:245] op_sel:[0,1]
	v_pk_mul_f32 v[108:109], v[108:109], v[244:245] op_sel:[0,1]
	v_pk_fma_f32 v[106:107], v[150:151], v[106:107], v[146:147]
	v_pk_fma_f32 v[108:109], v[152:153], v[108:109], v[148:149]
	v_cvt_pk_bf16_f32 v234, v106, v107
	v_cvt_pk_bf16_f32 v235, v108, v109
	v_cndmask_b32_e64 v234, v234, v249, s[0:1]
	v_cndmask_b32_e64 v235, v235, v249, s[0:1]
	v_permlane16_swap_b32_e32 v216, v218
	v_permlane16_swap_b32_e32 v217, v219
	s_nop 1
	v_permlane16_swap_b32_e32 v232, v234
	v_permlane16_swap_b32_e32 v233, v235
	global_store_dwordx4 v247, v[216:219], s[94:95] sc1
	global_store_dwordx4 v247, v[232:235], s[58:59] sc1
	v_cndmask_b32_e32 v240, v102, v248, vcc
	v_cndmask_b32_e32 v241, v103, v248, vcc
	v_cndmask_b32_e32 v242, v104, v248, vcc
	v_cndmask_b32_e32 v243, v105, v248, vcc
	v_cvt_pk_bf16_f32 v220, v240, v241
	v_cvt_pk_bf16_f32 v221, v242, v243
	v_pk_mul_f32 v[102:103], v[102:103], v[244:245] op_sel:[0,1]
	v_pk_mul_f32 v[104:105], v[104:105], v[244:245] op_sel:[0,1]
	v_pk_fma_f32 v[102:103], v[138:139], v[102:103], v[142:143]
	v_pk_fma_f32 v[104:105], v[140:141], v[104:105], v[144:145]
	v_cvt_pk_bf16_f32 v236, v102, v103
	v_cvt_pk_bf16_f32 v237, v104, v105
	v_cndmask_b32_e64 v236, v236, v249, s[0:1]
	v_cndmask_b32_e64 v237, v237, v249, s[0:1]
	v_cndmask_b32_e32 v240, v98, v248, vcc
	v_cndmask_b32_e32 v241, v99, v248, vcc
	v_cndmask_b32_e32 v242, v100, v248, vcc
	v_cndmask_b32_e32 v243, v101, v248, vcc
	v_cvt_pk_bf16_f32 v222, v240, v241
	v_cvt_pk_bf16_f32 v223, v242, v243
	v_pk_mul_f32 v[98:99], v[98:99], v[244:245] op_sel:[0,1]
	v_pk_mul_f32 v[100:101], v[100:101], v[244:245] op_sel:[0,1]
	v_pk_fma_f32 v[98:99], v[130:131], v[98:99], v[134:135]
	v_pk_fma_f32 v[100:101], v[132:133], v[100:101], v[136:137]
	v_cvt_pk_bf16_f32 v238, v98, v99
	v_cvt_pk_bf16_f32 v239, v100, v101
	v_cndmask_b32_e64 v238, v238, v249, s[0:1]
	v_cndmask_b32_e64 v239, v239, v249, s[0:1]
	v_permlane16_swap_b32_e32 v220, v222
	v_permlane16_swap_b32_e32 v221, v223
	s_nop 1
	v_permlane16_swap_b32_e32 v236, v238
	v_permlane16_swap_b32_e32 v237, v239
	global_store_dwordx4 v247, v[220:223], s[94:95] offset:256 sc1
	global_store_dwordx4 v247, v[236:239], s[58:59] offset:256 sc1
	ds_read_b64 v[244:245], v185 offset:8448
	v_add_u32_e32 v247, 0x10000, v246
	s_waitcnt lgkmcnt(0)
	v_cndmask_b32_e32 v240, v94, v248, vcc
	v_cndmask_b32_e32 v241, v95, v248, vcc
	v_cndmask_b32_e32 v242, v96, v248, vcc
	v_cndmask_b32_e32 v243, v97, v248, vcc
	v_cvt_pk_bf16_f32 v216, v240, v241
	v_cvt_pk_bf16_f32 v217, v242, v243
	v_pk_mul_f32 v[94:95], v[94:95], v[244:245] op_sel:[0,1]
	v_pk_mul_f32 v[96:97], v[96:97], v[244:245] op_sel:[0,1]
	v_pk_fma_f32 v[94:95], v[154:155], v[94:95], v[158:159]
	v_pk_fma_f32 v[96:97], v[156:157], v[96:97], v[160:161]
	v_cvt_pk_bf16_f32 v232, v94, v95
	v_cvt_pk_bf16_f32 v233, v96, v97
	v_cndmask_b32_e64 v232, v232, v249, s[0:1]
	v_cndmask_b32_e64 v233, v233, v249, s[0:1]
	v_cndmask_b32_e32 v240, v90, v248, vcc
	v_cndmask_b32_e32 v241, v91, v248, vcc
	v_cndmask_b32_e32 v242, v92, v248, vcc
	v_cndmask_b32_e32 v243, v93, v248, vcc
	v_cvt_pk_bf16_f32 v218, v240, v241
	v_cvt_pk_bf16_f32 v219, v242, v243
	v_pk_mul_f32 v[90:91], v[90:91], v[244:245] op_sel:[0,1]
	v_pk_mul_f32 v[92:93], v[92:93], v[244:245] op_sel:[0,1]
	v_pk_fma_f32 v[90:91], v[150:151], v[90:91], v[146:147]
	v_pk_fma_f32 v[92:93], v[152:153], v[92:93], v[148:149]
	v_cvt_pk_bf16_f32 v234, v90, v91
	v_cvt_pk_bf16_f32 v235, v92, v93
	v_cndmask_b32_e64 v234, v234, v249, s[0:1]
	v_cndmask_b32_e64 v235, v235, v249, s[0:1]
	v_permlane16_swap_b32_e32 v216, v218
	v_permlane16_swap_b32_e32 v217, v219
	s_nop 1
	v_permlane16_swap_b32_e32 v232, v234
	v_permlane16_swap_b32_e32 v233, v235
	global_store_dwordx4 v247, v[216:219], s[94:95] sc1
	global_store_dwordx4 v247, v[232:235], s[58:59] sc1
	v_cndmask_b32_e32 v240, v86, v248, vcc
	v_cndmask_b32_e32 v241, v87, v248, vcc
	v_cndmask_b32_e32 v242, v88, v248, vcc
	v_cndmask_b32_e32 v243, v89, v248, vcc
	v_cvt_pk_bf16_f32 v220, v240, v241
	v_cvt_pk_bf16_f32 v221, v242, v243
	v_pk_mul_f32 v[86:87], v[86:87], v[244:245] op_sel:[0,1]
	v_pk_mul_f32 v[88:89], v[88:89], v[244:245] op_sel:[0,1]
	v_pk_fma_f32 v[86:87], v[138:139], v[86:87], v[142:143]
	v_pk_fma_f32 v[88:89], v[140:141], v[88:89], v[144:145]
	v_cvt_pk_bf16_f32 v236, v86, v87
	v_cvt_pk_bf16_f32 v237, v88, v89
	v_cndmask_b32_e64 v236, v236, v249, s[0:1]
	v_cndmask_b32_e64 v237, v237, v249, s[0:1]
	v_cndmask_b32_e32 v240, v82, v248, vcc
	v_cndmask_b32_e32 v241, v83, v248, vcc
	v_cndmask_b32_e32 v242, v84, v248, vcc
	v_cndmask_b32_e32 v243, v85, v248, vcc
	v_cvt_pk_bf16_f32 v222, v240, v241
	v_cvt_pk_bf16_f32 v223, v242, v243
	v_pk_mul_f32 v[82:83], v[82:83], v[244:245] op_sel:[0,1]
	v_pk_mul_f32 v[84:85], v[84:85], v[244:245] op_sel:[0,1]
	v_pk_fma_f32 v[82:83], v[130:131], v[82:83], v[134:135]
	v_pk_fma_f32 v[84:85], v[132:133], v[84:85], v[136:137]
	v_cvt_pk_bf16_f32 v238, v82, v83
	v_cvt_pk_bf16_f32 v239, v84, v85
	v_cndmask_b32_e64 v238, v238, v249, s[0:1]
	v_cndmask_b32_e64 v239, v239, v249, s[0:1]
	v_permlane16_swap_b32_e32 v220, v222
	v_permlane16_swap_b32_e32 v221, v223
	s_nop 1
	v_permlane16_swap_b32_e32 v236, v238
	v_permlane16_swap_b32_e32 v237, v239
	global_store_dwordx4 v247, v[220:223], s[94:95] offset:256 sc1
	global_store_dwordx4 v247, v[236:239], s[58:59] offset:256 sc1
	ds_read_b64 v[244:245], v185 offset:8576
	v_add_u32_e32 v247, 0x18000, v246
	s_waitcnt lgkmcnt(0)
	v_cndmask_b32_e32 v240, v78, v248, vcc
	v_cndmask_b32_e32 v241, v79, v248, vcc
	v_cndmask_b32_e32 v242, v80, v248, vcc
	v_cndmask_b32_e32 v243, v81, v248, vcc
	v_cvt_pk_bf16_f32 v216, v240, v241
	v_cvt_pk_bf16_f32 v217, v242, v243
	v_pk_mul_f32 v[78:79], v[78:79], v[244:245] op_sel:[0,1]
	v_pk_mul_f32 v[80:81], v[80:81], v[244:245] op_sel:[0,1]
	v_pk_fma_f32 v[78:79], v[154:155], v[78:79], v[158:159]
	v_pk_fma_f32 v[80:81], v[156:157], v[80:81], v[160:161]
	v_cvt_pk_bf16_f32 v232, v78, v79
	v_cvt_pk_bf16_f32 v233, v80, v81
	v_cndmask_b32_e64 v232, v232, v249, s[0:1]
	v_cndmask_b32_e64 v233, v233, v249, s[0:1]
	v_cndmask_b32_e32 v240, v74, v248, vcc
	v_cndmask_b32_e32 v241, v75, v248, vcc
	v_cndmask_b32_e32 v242, v76, v248, vcc
	v_cndmask_b32_e32 v243, v77, v248, vcc
	v_cvt_pk_bf16_f32 v218, v240, v241
	v_cvt_pk_bf16_f32 v219, v242, v243
	v_pk_mul_f32 v[74:75], v[74:75], v[244:245] op_sel:[0,1]
	v_pk_mul_f32 v[76:77], v[76:77], v[244:245] op_sel:[0,1]
	v_pk_fma_f32 v[74:75], v[150:151], v[74:75], v[146:147]
	v_pk_fma_f32 v[76:77], v[152:153], v[76:77], v[148:149]
	v_cvt_pk_bf16_f32 v234, v74, v75
	v_cvt_pk_bf16_f32 v235, v76, v77
	v_cndmask_b32_e64 v234, v234, v249, s[0:1]
	v_cndmask_b32_e64 v235, v235, v249, s[0:1]
	v_permlane16_swap_b32_e32 v216, v218
	v_permlane16_swap_b32_e32 v217, v219
	s_nop 1
	v_permlane16_swap_b32_e32 v232, v234
	v_permlane16_swap_b32_e32 v233, v235
	global_store_dwordx4 v247, v[216:219], s[94:95] sc1
	global_store_dwordx4 v247, v[232:235], s[58:59] sc1
	v_cndmask_b32_e32 v240, v70, v248, vcc
	v_cndmask_b32_e32 v241, v71, v248, vcc
	v_cndmask_b32_e32 v242, v72, v248, vcc
	v_cndmask_b32_e32 v243, v73, v248, vcc
	v_cvt_pk_bf16_f32 v220, v240, v241
	v_cvt_pk_bf16_f32 v221, v242, v243
	v_pk_mul_f32 v[70:71], v[70:71], v[244:245] op_sel:[0,1]
	v_pk_mul_f32 v[72:73], v[72:73], v[244:245] op_sel:[0,1]
	v_pk_fma_f32 v[70:71], v[138:139], v[70:71], v[142:143]
	v_pk_fma_f32 v[72:73], v[140:141], v[72:73], v[144:145]
	v_cvt_pk_bf16_f32 v236, v70, v71
	v_cvt_pk_bf16_f32 v237, v72, v73
	v_cndmask_b32_e64 v236, v236, v249, s[0:1]
	v_cndmask_b32_e64 v237, v237, v249, s[0:1]
	v_cndmask_b32_e32 v240, v66, v248, vcc
	v_cndmask_b32_e32 v241, v67, v248, vcc
	v_cndmask_b32_e32 v242, v68, v248, vcc
	v_cndmask_b32_e32 v243, v69, v248, vcc
	v_cvt_pk_bf16_f32 v222, v240, v241
	v_cvt_pk_bf16_f32 v223, v242, v243
	v_pk_mul_f32 v[66:67], v[66:67], v[244:245] op_sel:[0,1]
	v_pk_mul_f32 v[68:69], v[68:69], v[244:245] op_sel:[0,1]
	v_pk_fma_f32 v[66:67], v[130:131], v[66:67], v[134:135]
	v_pk_fma_f32 v[68:69], v[132:133], v[68:69], v[136:137]
	v_cvt_pk_bf16_f32 v238, v66, v67
	v_cvt_pk_bf16_f32 v239, v68, v69
	v_cndmask_b32_e64 v238, v238, v249, s[0:1]
	v_cndmask_b32_e64 v239, v239, v249, s[0:1]
	v_permlane16_swap_b32_e32 v220, v222
	v_permlane16_swap_b32_e32 v221, v223
	s_nop 1
	v_permlane16_swap_b32_e32 v236, v238
	v_permlane16_swap_b32_e32 v237, v239
	global_store_dwordx4 v247, v[220:223], s[94:95] offset:256 sc1
	global_store_dwordx4 v247, v[236:239], s[58:59] offset:256 sc1
	ds_read_b64 v[244:245], v185 offset:9216
	v_add_u32_e32 v247, 0x40000, v246
	s_waitcnt lgkmcnt(0)
	v_cndmask_b32_e32 v240, v62, v248, vcc
	v_cndmask_b32_e32 v241, v63, v248, vcc
	v_cndmask_b32_e32 v242, v64, v248, vcc
	v_cndmask_b32_e32 v243, v65, v248, vcc
	v_cvt_pk_bf16_f32 v216, v240, v241
	v_cvt_pk_bf16_f32 v217, v242, v243
	v_pk_mul_f32 v[62:63], v[62:63], v[244:245] op_sel:[0,1]
	v_pk_mul_f32 v[64:65], v[64:65], v[244:245] op_sel:[0,1]
	v_pk_fma_f32 v[62:63], v[154:155], v[62:63], v[158:159]
	v_pk_fma_f32 v[64:65], v[156:157], v[64:65], v[160:161]
	v_cvt_pk_bf16_f32 v232, v62, v63
	v_cvt_pk_bf16_f32 v233, v64, v65
	v_cndmask_b32_e64 v232, v232, v249, s[0:1]
	v_cndmask_b32_e64 v233, v233, v249, s[0:1]
	v_cndmask_b32_e32 v240, v58, v248, vcc
	v_cndmask_b32_e32 v241, v59, v248, vcc
	v_cndmask_b32_e32 v242, v60, v248, vcc
	v_cndmask_b32_e32 v243, v61, v248, vcc
	v_cvt_pk_bf16_f32 v218, v240, v241
	v_cvt_pk_bf16_f32 v219, v242, v243
	v_pk_mul_f32 v[58:59], v[58:59], v[244:245] op_sel:[0,1]
	v_pk_mul_f32 v[60:61], v[60:61], v[244:245] op_sel:[0,1]
	v_pk_fma_f32 v[58:59], v[150:151], v[58:59], v[146:147]
	v_pk_fma_f32 v[60:61], v[152:153], v[60:61], v[148:149]
	v_cvt_pk_bf16_f32 v234, v58, v59
	v_cvt_pk_bf16_f32 v235, v60, v61
	v_cndmask_b32_e64 v234, v234, v249, s[0:1]
	v_cndmask_b32_e64 v235, v235, v249, s[0:1]
	v_permlane16_swap_b32_e32 v216, v218
	v_permlane16_swap_b32_e32 v217, v219
	s_nop 1
	v_permlane16_swap_b32_e32 v232, v234
	v_permlane16_swap_b32_e32 v233, v235
	global_store_dwordx4 v247, v[216:219], s[94:95] sc1
	global_store_dwordx4 v247, v[232:235], s[58:59] sc1
	v_cndmask_b32_e32 v240, v54, v248, vcc
	v_cndmask_b32_e32 v241, v55, v248, vcc
	v_cndmask_b32_e32 v242, v56, v248, vcc
	v_cndmask_b32_e32 v243, v57, v248, vcc
	v_cvt_pk_bf16_f32 v220, v240, v241
	v_cvt_pk_bf16_f32 v221, v242, v243
	v_pk_mul_f32 v[54:55], v[54:55], v[244:245] op_sel:[0,1]
	v_pk_mul_f32 v[56:57], v[56:57], v[244:245] op_sel:[0,1]
	v_pk_fma_f32 v[54:55], v[138:139], v[54:55], v[142:143]
	v_pk_fma_f32 v[56:57], v[140:141], v[56:57], v[144:145]
	v_cvt_pk_bf16_f32 v236, v54, v55
	v_cvt_pk_bf16_f32 v237, v56, v57
	v_cndmask_b32_e64 v236, v236, v249, s[0:1]
	v_cndmask_b32_e64 v237, v237, v249, s[0:1]
	v_cndmask_b32_e32 v240, v50, v248, vcc
	v_cndmask_b32_e32 v241, v51, v248, vcc
	v_cndmask_b32_e32 v242, v52, v248, vcc
	v_cndmask_b32_e32 v243, v53, v248, vcc
	v_cvt_pk_bf16_f32 v222, v240, v241
	v_cvt_pk_bf16_f32 v223, v242, v243
	v_pk_mul_f32 v[50:51], v[50:51], v[244:245] op_sel:[0,1]
	v_pk_mul_f32 v[52:53], v[52:53], v[244:245] op_sel:[0,1]
	v_pk_fma_f32 v[50:51], v[130:131], v[50:51], v[134:135]
	v_pk_fma_f32 v[52:53], v[132:133], v[52:53], v[136:137]
	v_cvt_pk_bf16_f32 v238, v50, v51
	v_cvt_pk_bf16_f32 v239, v52, v53
	v_cndmask_b32_e64 v238, v238, v249, s[0:1]
	v_cndmask_b32_e64 v239, v239, v249, s[0:1]
	v_permlane16_swap_b32_e32 v220, v222
	v_permlane16_swap_b32_e32 v221, v223
	s_nop 1
	v_permlane16_swap_b32_e32 v236, v238
	v_permlane16_swap_b32_e32 v237, v239
	global_store_dwordx4 v247, v[220:223], s[94:95] offset:256 sc1
	global_store_dwordx4 v247, v[236:239], s[58:59] offset:256 sc1
	ds_read_b64 v[244:245], v185 offset:9344
	v_add_u32_e32 v247, 0x48000, v246
	s_waitcnt lgkmcnt(0)
	v_cndmask_b32_e32 v240, v46, v248, vcc
	v_cndmask_b32_e32 v241, v47, v248, vcc
	v_cndmask_b32_e32 v242, v48, v248, vcc
	v_cndmask_b32_e32 v243, v49, v248, vcc
	v_cvt_pk_bf16_f32 v216, v240, v241
	v_cvt_pk_bf16_f32 v217, v242, v243
	v_pk_mul_f32 v[46:47], v[46:47], v[244:245] op_sel:[0,1]
	v_pk_mul_f32 v[48:49], v[48:49], v[244:245] op_sel:[0,1]
	v_pk_fma_f32 v[46:47], v[154:155], v[46:47], v[158:159]
	v_pk_fma_f32 v[48:49], v[156:157], v[48:49], v[160:161]
	v_cvt_pk_bf16_f32 v232, v46, v47
	v_cvt_pk_bf16_f32 v233, v48, v49
	v_cndmask_b32_e64 v232, v232, v249, s[0:1]
	v_cndmask_b32_e64 v233, v233, v249, s[0:1]
	v_cndmask_b32_e32 v240, v42, v248, vcc
	v_cndmask_b32_e32 v241, v43, v248, vcc
	v_cndmask_b32_e32 v242, v44, v248, vcc
	v_cndmask_b32_e32 v243, v45, v248, vcc
	v_cvt_pk_bf16_f32 v218, v240, v241
	v_cvt_pk_bf16_f32 v219, v242, v243
	v_pk_mul_f32 v[42:43], v[42:43], v[244:245] op_sel:[0,1]
	v_pk_mul_f32 v[44:45], v[44:45], v[244:245] op_sel:[0,1]
	v_pk_fma_f32 v[42:43], v[150:151], v[42:43], v[146:147]
	v_pk_fma_f32 v[44:45], v[152:153], v[44:45], v[148:149]
	v_cvt_pk_bf16_f32 v234, v42, v43
	v_cvt_pk_bf16_f32 v235, v44, v45
	v_cndmask_b32_e64 v234, v234, v249, s[0:1]
	v_cndmask_b32_e64 v235, v235, v249, s[0:1]
	v_permlane16_swap_b32_e32 v216, v218
	v_permlane16_swap_b32_e32 v217, v219
	s_nop 1
	v_permlane16_swap_b32_e32 v232, v234
	v_permlane16_swap_b32_e32 v233, v235
	global_store_dwordx4 v247, v[216:219], s[94:95] sc1
	global_store_dwordx4 v247, v[232:235], s[58:59] sc1
	v_cndmask_b32_e32 v240, v38, v248, vcc
	v_cndmask_b32_e32 v241, v39, v248, vcc
	v_cndmask_b32_e32 v242, v40, v248, vcc
	v_cndmask_b32_e32 v243, v41, v248, vcc
	v_cvt_pk_bf16_f32 v220, v240, v241
	v_cvt_pk_bf16_f32 v221, v242, v243
	v_pk_mul_f32 v[38:39], v[38:39], v[244:245] op_sel:[0,1]
	v_pk_mul_f32 v[40:41], v[40:41], v[244:245] op_sel:[0,1]
	v_pk_fma_f32 v[38:39], v[138:139], v[38:39], v[142:143]
	v_pk_fma_f32 v[40:41], v[140:141], v[40:41], v[144:145]
	v_cvt_pk_bf16_f32 v236, v38, v39
	v_cvt_pk_bf16_f32 v237, v40, v41
	v_cndmask_b32_e64 v236, v236, v249, s[0:1]
	v_cndmask_b32_e64 v237, v237, v249, s[0:1]
	v_cndmask_b32_e32 v240, v34, v248, vcc
	v_cndmask_b32_e32 v241, v35, v248, vcc
	v_cndmask_b32_e32 v242, v36, v248, vcc
	v_cndmask_b32_e32 v243, v37, v248, vcc
	v_cvt_pk_bf16_f32 v222, v240, v241
	v_cvt_pk_bf16_f32 v223, v242, v243
	v_pk_mul_f32 v[34:35], v[34:35], v[244:245] op_sel:[0,1]
	v_pk_mul_f32 v[36:37], v[36:37], v[244:245] op_sel:[0,1]
	v_pk_fma_f32 v[34:35], v[130:131], v[34:35], v[134:135]
	v_pk_fma_f32 v[36:37], v[132:133], v[36:37], v[136:137]
	v_cvt_pk_bf16_f32 v238, v34, v35
	v_cvt_pk_bf16_f32 v239, v36, v37
	v_cndmask_b32_e64 v238, v238, v249, s[0:1]
	v_cndmask_b32_e64 v239, v239, v249, s[0:1]
	v_permlane16_swap_b32_e32 v220, v222
	v_permlane16_swap_b32_e32 v221, v223
	s_nop 1
	v_permlane16_swap_b32_e32 v236, v238
	v_permlane16_swap_b32_e32 v237, v239
	global_store_dwordx4 v247, v[220:223], s[94:95] offset:256 sc1
	global_store_dwordx4 v247, v[236:239], s[58:59] offset:256 sc1
	ds_read_b64 v[244:245], v185 offset:9472
	v_add_u32_e32 v247, 0x50000, v246
	s_waitcnt lgkmcnt(0)
	v_cndmask_b32_e32 v240, v30, v248, vcc
	v_cndmask_b32_e32 v241, v31, v248, vcc
	v_cndmask_b32_e32 v242, v32, v248, vcc
	v_cndmask_b32_e32 v243, v33, v248, vcc
	v_cvt_pk_bf16_f32 v216, v240, v241
	v_cvt_pk_bf16_f32 v217, v242, v243
	v_pk_mul_f32 v[30:31], v[30:31], v[244:245] op_sel:[0,1]
	v_pk_mul_f32 v[32:33], v[32:33], v[244:245] op_sel:[0,1]
	v_pk_fma_f32 v[30:31], v[154:155], v[30:31], v[158:159]
	v_pk_fma_f32 v[32:33], v[156:157], v[32:33], v[160:161]
	v_cvt_pk_bf16_f32 v232, v30, v31
	v_cvt_pk_bf16_f32 v233, v32, v33
	v_cndmask_b32_e64 v232, v232, v249, s[0:1]
	v_cndmask_b32_e64 v233, v233, v249, s[0:1]
	v_cndmask_b32_e32 v240, v26, v248, vcc
	v_cndmask_b32_e32 v241, v27, v248, vcc
	v_cndmask_b32_e32 v242, v28, v248, vcc
	v_cndmask_b32_e32 v243, v29, v248, vcc
	v_cvt_pk_bf16_f32 v218, v240, v241
	v_cvt_pk_bf16_f32 v219, v242, v243
	v_pk_mul_f32 v[26:27], v[26:27], v[244:245] op_sel:[0,1]
	v_pk_mul_f32 v[28:29], v[28:29], v[244:245] op_sel:[0,1]
	v_pk_fma_f32 v[26:27], v[150:151], v[26:27], v[146:147]
	v_pk_fma_f32 v[28:29], v[152:153], v[28:29], v[148:149]
	v_cvt_pk_bf16_f32 v234, v26, v27
	v_cvt_pk_bf16_f32 v235, v28, v29
	v_cndmask_b32_e64 v234, v234, v249, s[0:1]
	v_cndmask_b32_e64 v235, v235, v249, s[0:1]
	v_permlane16_swap_b32_e32 v216, v218
	v_permlane16_swap_b32_e32 v217, v219
	s_nop 1
	v_permlane16_swap_b32_e32 v232, v234
	v_permlane16_swap_b32_e32 v233, v235
	global_store_dwordx4 v247, v[216:219], s[94:95] sc1
	global_store_dwordx4 v247, v[232:235], s[58:59] sc1
	v_cndmask_b32_e32 v240, v22, v248, vcc
	v_cndmask_b32_e32 v241, v23, v248, vcc
	v_cndmask_b32_e32 v242, v24, v248, vcc
	v_cndmask_b32_e32 v243, v25, v248, vcc
	v_cvt_pk_bf16_f32 v220, v240, v241
	v_cvt_pk_bf16_f32 v221, v242, v243
	v_pk_mul_f32 v[22:23], v[22:23], v[244:245] op_sel:[0,1]
	v_pk_mul_f32 v[24:25], v[24:25], v[244:245] op_sel:[0,1]
	v_pk_fma_f32 v[22:23], v[138:139], v[22:23], v[142:143]
	v_pk_fma_f32 v[24:25], v[140:141], v[24:25], v[144:145]
	v_cvt_pk_bf16_f32 v236, v22, v23
	v_cvt_pk_bf16_f32 v237, v24, v25
	v_cndmask_b32_e64 v236, v236, v249, s[0:1]
	v_cndmask_b32_e64 v237, v237, v249, s[0:1]
	v_cndmask_b32_e32 v240, v18, v248, vcc
	v_cndmask_b32_e32 v241, v19, v248, vcc
	v_cndmask_b32_e32 v242, v20, v248, vcc
	v_cndmask_b32_e32 v243, v21, v248, vcc
	v_cvt_pk_bf16_f32 v222, v240, v241
	v_cvt_pk_bf16_f32 v223, v242, v243
	v_pk_mul_f32 v[18:19], v[18:19], v[244:245] op_sel:[0,1]
	v_pk_mul_f32 v[20:21], v[20:21], v[244:245] op_sel:[0,1]
	v_pk_fma_f32 v[18:19], v[130:131], v[18:19], v[134:135]
	v_pk_fma_f32 v[20:21], v[132:133], v[20:21], v[136:137]
	v_cvt_pk_bf16_f32 v238, v18, v19
	v_cvt_pk_bf16_f32 v239, v20, v21
	v_cndmask_b32_e64 v238, v238, v249, s[0:1]
	v_cndmask_b32_e64 v239, v239, v249, s[0:1]
	v_permlane16_swap_b32_e32 v220, v222
	v_permlane16_swap_b32_e32 v221, v223
	s_nop 1
	v_permlane16_swap_b32_e32 v236, v238
	v_permlane16_swap_b32_e32 v237, v239
	global_store_dwordx4 v247, v[220:223], s[94:95] offset:256 sc1
	global_store_dwordx4 v247, v[236:239], s[58:59] offset:256 sc1
	ds_read_b64 v[244:245], v185 offset:9600
	v_add_u32_e32 v247, 0x58000, v246
	s_waitcnt lgkmcnt(0)
	v_cndmask_b32_e32 v240, v14, v248, vcc
	v_cndmask_b32_e32 v241, v15, v248, vcc
	v_cndmask_b32_e32 v242, v16, v248, vcc
	v_cndmask_b32_e32 v243, v17, v248, vcc
	v_cvt_pk_bf16_f32 v216, v240, v241
	v_cvt_pk_bf16_f32 v217, v242, v243
	v_pk_mul_f32 v[14:15], v[14:15], v[244:245] op_sel:[0,1]
	v_pk_mul_f32 v[16:17], v[16:17], v[244:245] op_sel:[0,1]
	v_pk_fma_f32 v[14:15], v[154:155], v[14:15], v[158:159]
	v_pk_fma_f32 v[16:17], v[156:157], v[16:17], v[160:161]
	v_cvt_pk_bf16_f32 v232, v14, v15
	v_cvt_pk_bf16_f32 v233, v16, v17
	v_cndmask_b32_e64 v232, v232, v249, s[0:1]
	v_cndmask_b32_e64 v233, v233, v249, s[0:1]
	v_cndmask_b32_e32 v240, v10, v248, vcc
	v_cndmask_b32_e32 v241, v11, v248, vcc
	v_cndmask_b32_e32 v242, v12, v248, vcc
	v_cndmask_b32_e32 v243, v13, v248, vcc
	v_cvt_pk_bf16_f32 v218, v240, v241
	v_cvt_pk_bf16_f32 v219, v242, v243
	v_pk_mul_f32 v[10:11], v[10:11], v[244:245] op_sel:[0,1]
	v_pk_mul_f32 v[12:13], v[12:13], v[244:245] op_sel:[0,1]
	v_pk_fma_f32 v[10:11], v[150:151], v[10:11], v[146:147]
	v_pk_fma_f32 v[12:13], v[152:153], v[12:13], v[148:149]
	v_cvt_pk_bf16_f32 v234, v10, v11
	v_cvt_pk_bf16_f32 v235, v12, v13
	v_cndmask_b32_e64 v234, v234, v249, s[0:1]
	v_cndmask_b32_e64 v235, v235, v249, s[0:1]
	v_permlane16_swap_b32_e32 v216, v218
	v_permlane16_swap_b32_e32 v217, v219
	s_nop 1
	v_permlane16_swap_b32_e32 v232, v234
	v_permlane16_swap_b32_e32 v233, v235
	global_store_dwordx4 v247, v[216:219], s[94:95] sc1
	global_store_dwordx4 v247, v[232:235], s[58:59] sc1
	v_cndmask_b32_e32 v240, v6, v248, vcc
	v_cndmask_b32_e32 v241, v7, v248, vcc
	v_cndmask_b32_e32 v242, v8, v248, vcc
	v_cndmask_b32_e32 v243, v9, v248, vcc
	v_cvt_pk_bf16_f32 v220, v240, v241
	v_cvt_pk_bf16_f32 v221, v242, v243
	v_pk_mul_f32 v[6:7], v[6:7], v[244:245] op_sel:[0,1]
	v_pk_mul_f32 v[8:9], v[8:9], v[244:245] op_sel:[0,1]
	v_pk_fma_f32 v[6:7], v[138:139], v[6:7], v[142:143]
	v_pk_fma_f32 v[8:9], v[140:141], v[8:9], v[144:145]
	v_cvt_pk_bf16_f32 v236, v6, v7
	v_cvt_pk_bf16_f32 v237, v8, v9
	v_cndmask_b32_e64 v236, v236, v249, s[0:1]
	v_cndmask_b32_e64 v237, v237, v249, s[0:1]
	v_cndmask_b32_e32 v240, v2, v248, vcc
	v_cndmask_b32_e32 v241, v3, v248, vcc
	v_cndmask_b32_e32 v242, v4, v248, vcc
	v_cndmask_b32_e32 v243, v5, v248, vcc
	v_cvt_pk_bf16_f32 v222, v240, v241
	v_cvt_pk_bf16_f32 v223, v242, v243
	v_pk_mul_f32 v[2:3], v[2:3], v[244:245] op_sel:[0,1]
	v_pk_mul_f32 v[4:5], v[4:5], v[244:245] op_sel:[0,1]
	v_pk_fma_f32 v[2:3], v[130:131], v[2:3], v[134:135]
	v_pk_fma_f32 v[4:5], v[132:133], v[4:5], v[136:137]
	v_cvt_pk_bf16_f32 v238, v2, v3
	v_cvt_pk_bf16_f32 v239, v4, v5
	v_cndmask_b32_e64 v238, v238, v249, s[0:1]
	v_cndmask_b32_e64 v239, v239, v249, s[0:1]
	v_permlane16_swap_b32_e32 v220, v222
	v_permlane16_swap_b32_e32 v221, v223
	s_nop 1
	v_permlane16_swap_b32_e32 v236, v238
	v_permlane16_swap_b32_e32 v237, v239
	global_store_dwordx4 v247, v[220:223], s[94:95] offset:256 sc1
	global_store_dwordx4 v247, v[236:239], s[58:59] offset:256 sc1

.LBB0_1531:
	s_or_b64 exec, exec, s[6:7]
	s_waitcnt lgkmcnt(1)
	v_add_co_u32_e32 v132, vcc, 0x10e000, v148
	s_mov_b64 s[0:1], 0x10e000
	s_nop 0
	v_addc_co_u32_e32 v133, vcc, 0, v149, vcc
	v_lshl_add_u64 v[130:131], v[148:149], 0, s[0:1]
	s_mov_b64 s[0:1], 0x110000
	v_add_co_u32_e32 v136, vcc, 0x110000, v148
	s_waitcnt lgkmcnt(0)
	s_barrier
	v_lshl_add_u64 v[134:135], v[148:149], 0, s[0:1]
	v_addc_co_u32_e32 v137, vcc, 0, v149, vcc
	global_load_dwordx4 v[146:149], v[134:135], off offset:64
	global_load_dwordx4 v[150:153], v[130:131], off offset:64
	global_load_dwordx4 v[138:141], v[130:131], off offset:512
	global_load_dwordx4 v[142:145], v[134:135], off offset:512
	global_load_dwordx4 v[154:157], v[132:133], off
	global_load_dwordx4 v[158:161], v[136:137], off
	s_nop 0
	global_load_dwordx4 v[130:133], v[130:131], off offset:576
	s_nop 0
	global_load_dwordx4 v[134:137], v[134:135], off offset:576
	v_or_b32_e32 v224, v184, v182
	s_waitcnt lgkmcnt(0)
	v_or_b32_e32 v225, v186, v224
	v_mov_b32_e32 v248, 0x7fc00000
	v_mov_b32_e32 v249, 0x7fc07fc0
	v_cmp_ne_u32_e32 vcc, 0, v224
	v_cmp_ne_u32_e64 s[0:1], 0, v225
	v_add_u32_e32 v246, v180, v162
	v_lshlrev_b32_e32 v246, 1, v246
	v_and_b32_e32 v247, 16, v0
	v_lshrrev_b32_e32 v247, 1, v247
	v_mad_u32_u24 v246, v247, 3, v246
	s_waitcnt vmcnt(0)
	ds_read_b64 v[244:245], v183 offset:8192
	s_waitcnt lgkmcnt(0)
	v_cndmask_b32_e32 v240, v118, v248, vcc
	v_cndmask_b32_e32 v241, v119, v248, vcc
	v_cndmask_b32_e32 v242, v120, v248, vcc
	v_cndmask_b32_e32 v243, v121, v248, vcc
	v_cvt_pk_bf16_f32 v216, v240, v241
	v_cvt_pk_bf16_f32 v217, v242, v243
	v_pk_mul_f32 v[118:119], v[118:119], v[244:245] op_sel:[0,1]
	v_pk_mul_f32 v[120:121], v[120:121], v[244:245] op_sel:[0,1]
	v_pk_fma_f32 v[118:119], v[154:155], v[118:119], v[158:159]
	v_pk_fma_f32 v[120:121], v[156:157], v[120:121], v[160:161]
	v_cvt_pk_bf16_f32 v232, v118, v119
	v_cvt_pk_bf16_f32 v233, v120, v121
	v_cndmask_b32_e64 v232, v232, v249, s[0:1]
	v_cndmask_b32_e64 v233, v233, v249, s[0:1]
	v_cndmask_b32_e32 v240, v122, v248, vcc
	v_cndmask_b32_e32 v241, v123, v248, vcc
	v_cndmask_b32_e32 v242, v124, v248, vcc
	v_cndmask_b32_e32 v243, v125, v248, vcc
	v_cvt_pk_bf16_f32 v218, v240, v241
	v_cvt_pk_bf16_f32 v219, v242, v243
	v_pk_mul_f32 v[122:123], v[122:123], v[244:245] op_sel:[0,1]
	v_pk_mul_f32 v[124:125], v[124:125], v[244:245] op_sel:[0,1]
	v_pk_fma_f32 v[122:123], v[150:151], v[122:123], v[146:147]
	v_pk_fma_f32 v[124:125], v[152:153], v[124:125], v[148:149]
	v_cvt_pk_bf16_f32 v234, v122, v123
	v_cvt_pk_bf16_f32 v235, v124, v125
	v_cndmask_b32_e64 v234, v234, v249, s[0:1]
	v_cndmask_b32_e64 v235, v235, v249, s[0:1]
	v_permlane16_swap_b32_e32 v216, v218
	v_permlane16_swap_b32_e32 v217, v219
	s_nop 1
	v_permlane16_swap_b32_e32 v232, v234
	v_permlane16_swap_b32_e32 v233, v235
	global_store_dwordx4 v246, v[216:219], s[56:57] sc1
	global_store_dwordx4 v246, v[232:235], s[58:59] sc1
	v_cndmask_b32_e32 v240, v126, v248, vcc
	v_cndmask_b32_e32 v241, v127, v248, vcc
	v_cndmask_b32_e32 v242, v128, v248, vcc
	v_cndmask_b32_e32 v243, v129, v248, vcc
	v_cvt_pk_bf16_f32 v220, v240, v241
	v_cvt_pk_bf16_f32 v221, v242, v243
	v_pk_mul_f32 v[126:127], v[126:127], v[244:245] op_sel:[0,1]
	v_pk_mul_f32 v[128:129], v[128:129], v[244:245] op_sel:[0,1]
	v_pk_fma_f32 v[126:127], v[138:139], v[126:127], v[142:143]
	v_pk_fma_f32 v[128:129], v[140:141], v[128:129], v[144:145]
	v_cvt_pk_bf16_f32 v236, v126, v127
	v_cvt_pk_bf16_f32 v237, v128, v129
	v_cndmask_b32_e64 v236, v236, v249, s[0:1]
	v_cndmask_b32_e64 v237, v237, v249, s[0:1]
	v_cndmask_b32_e32 v240, v114, v248, vcc
	v_cndmask_b32_e32 v241, v115, v248, vcc
	v_cndmask_b32_e32 v242, v116, v248, vcc
	v_cndmask_b32_e32 v243, v117, v248, vcc
	v_cvt_pk_bf16_f32 v222, v240, v241
	v_cvt_pk_bf16_f32 v223, v242, v243
	v_pk_mul_f32 v[114:115], v[114:115], v[244:245] op_sel:[0,1]
	v_pk_mul_f32 v[116:117], v[116:117], v[244:245] op_sel:[0,1]
	v_pk_fma_f32 v[114:115], v[130:131], v[114:115], v[134:135]
	v_pk_fma_f32 v[116:117], v[132:133], v[116:117], v[136:137]
	v_cvt_pk_bf16_f32 v238, v114, v115
	v_cvt_pk_bf16_f32 v239, v116, v117
	v_cndmask_b32_e64 v238, v238, v249, s[0:1]
	v_cndmask_b32_e64 v239, v239, v249, s[0:1]
	v_permlane16_swap_b32_e32 v220, v222
	v_permlane16_swap_b32_e32 v221, v223
	s_nop 1
	v_permlane16_swap_b32_e32 v236, v238
	v_permlane16_swap_b32_e32 v237, v239
	global_store_dwordx4 v246, v[220:223], s[56:57] offset:256 sc1
	global_store_dwordx4 v246, v[236:239], s[58:59] offset:256 sc1
	ds_read_b64 v[244:245], v183 offset:8320
	v_add_u32_e32 v247, 0x8000, v246
	s_waitcnt lgkmcnt(0)
	v_cndmask_b32_e32 v240, v110, v248, vcc
	v_cndmask_b32_e32 v241, v111, v248, vcc
	v_cndmask_b32_e32 v242, v112, v248, vcc
	v_cndmask_b32_e32 v243, v113, v248, vcc
	v_cvt_pk_bf16_f32 v216, v240, v241
	v_cvt_pk_bf16_f32 v217, v242, v243
	v_pk_mul_f32 v[110:111], v[110:111], v[244:245] op_sel:[0,1]
	v_pk_mul_f32 v[112:113], v[112:113], v[244:245] op_sel:[0,1]
	v_pk_fma_f32 v[110:111], v[154:155], v[110:111], v[158:159]
	v_pk_fma_f32 v[112:113], v[156:157], v[112:113], v[160:161]
	v_cvt_pk_bf16_f32 v232, v110, v111
	v_cvt_pk_bf16_f32 v233, v112, v113
	v_cndmask_b32_e64 v232, v232, v249, s[0:1]
	v_cndmask_b32_e64 v233, v233, v249, s[0:1]
	v_cndmask_b32_e32 v240, v106, v248, vcc
	v_cndmask_b32_e32 v241, v107, v248, vcc
	v_cndmask_b32_e32 v242, v108, v248, vcc
	v_cndmask_b32_e32 v243, v109, v248, vcc
	v_cvt_pk_bf16_f32 v218, v240, v241
	v_cvt_pk_bf16_f32 v219, v242, v243
	v_pk_mul_f32 v[106:107], v[106:107], v[244:245] op_sel:[0,1]
	v_pk_mul_f32 v[108:109], v[108:109], v[244:245] op_sel:[0,1]
	v_pk_fma_f32 v[106:107], v[150:151], v[106:107], v[146:147]
	v_pk_fma_f32 v[108:109], v[152:153], v[108:109], v[148:149]
	v_cvt_pk_bf16_f32 v234, v106, v107
	v_cvt_pk_bf16_f32 v235, v108, v109
	v_cndmask_b32_e64 v234, v234, v249, s[0:1]
	v_cndmask_b32_e64 v235, v235, v249, s[0:1]
	v_permlane16_swap_b32_e32 v216, v218
	v_permlane16_swap_b32_e32 v217, v219
	s_nop 1
	v_permlane16_swap_b32_e32 v232, v234
	v_permlane16_swap_b32_e32 v233, v235
	global_store_dwordx4 v247, v[216:219], s[56:57] sc1
	global_store_dwordx4 v247, v[232:235], s[58:59] sc1
	v_cndmask_b32_e32 v240, v102, v248, vcc
	v_cndmask_b32_e32 v241, v103, v248, vcc
	v_cndmask_b32_e32 v242, v104, v248, vcc
	v_cndmask_b32_e32 v243, v105, v248, vcc
	v_cvt_pk_bf16_f32 v220, v240, v241
	v_cvt_pk_bf16_f32 v221, v242, v243
	v_pk_mul_f32 v[102:103], v[102:103], v[244:245] op_sel:[0,1]
	v_pk_mul_f32 v[104:105], v[104:105], v[244:245] op_sel:[0,1]
	v_pk_fma_f32 v[102:103], v[138:139], v[102:103], v[142:143]
	v_pk_fma_f32 v[104:105], v[140:141], v[104:105], v[144:145]
	v_cvt_pk_bf16_f32 v236, v102, v103
	v_cvt_pk_bf16_f32 v237, v104, v105
	v_cndmask_b32_e64 v236, v236, v249, s[0:1]
	v_cndmask_b32_e64 v237, v237, v249, s[0:1]
	v_cndmask_b32_e32 v240, v98, v248, vcc
	v_cndmask_b32_e32 v241, v99, v248, vcc
	v_cndmask_b32_e32 v242, v100, v248, vcc
	v_cndmask_b32_e32 v243, v101, v248, vcc
	v_cvt_pk_bf16_f32 v222, v240, v241
	v_cvt_pk_bf16_f32 v223, v242, v243
	v_pk_mul_f32 v[98:99], v[98:99], v[244:245] op_sel:[0,1]
	v_pk_mul_f32 v[100:101], v[100:101], v[244:245] op_sel:[0,1]
	v_pk_fma_f32 v[98:99], v[130:131], v[98:99], v[134:135]
	v_pk_fma_f32 v[100:101], v[132:133], v[100:101], v[136:137]
	v_cvt_pk_bf16_f32 v238, v98, v99
	v_cvt_pk_bf16_f32 v239, v100, v101
	v_cndmask_b32_e64 v238, v238, v249, s[0:1]
	v_cndmask_b32_e64 v239, v239, v249, s[0:1]
	v_permlane16_swap_b32_e32 v220, v222
	v_permlane16_swap_b32_e32 v221, v223
	s_nop 1
	v_permlane16_swap_b32_e32 v236, v238
	v_permlane16_swap_b32_e32 v237, v239
	global_store_dwordx4 v247, v[220:223], s[56:57] offset:256 sc1
	global_store_dwordx4 v247, v[236:239], s[58:59] offset:256 sc1
	ds_read_b64 v[244:245], v183 offset:8448
	v_add_u32_e32 v247, 0x10000, v246
	s_waitcnt lgkmcnt(0)
	v_cndmask_b32_e32 v240, v94, v248, vcc
	v_cndmask_b32_e32 v241, v95, v248, vcc
	v_cndmask_b32_e32 v242, v96, v248, vcc
	v_cndmask_b32_e32 v243, v97, v248, vcc
	v_cvt_pk_bf16_f32 v216, v240, v241
	v_cvt_pk_bf16_f32 v217, v242, v243
	v_pk_mul_f32 v[94:95], v[94:95], v[244:245] op_sel:[0,1]
	v_pk_mul_f32 v[96:97], v[96:97], v[244:245] op_sel:[0,1]
	v_pk_fma_f32 v[94:95], v[154:155], v[94:95], v[158:159]
	v_pk_fma_f32 v[96:97], v[156:157], v[96:97], v[160:161]
	v_cvt_pk_bf16_f32 v232, v94, v95
	v_cvt_pk_bf16_f32 v233, v96, v97
	v_cndmask_b32_e64 v232, v232, v249, s[0:1]
	v_cndmask_b32_e64 v233, v233, v249, s[0:1]
	v_cndmask_b32_e32 v240, v90, v248, vcc
	v_cndmask_b32_e32 v241, v91, v248, vcc
	v_cndmask_b32_e32 v242, v92, v248, vcc
	v_cndmask_b32_e32 v243, v93, v248, vcc
	v_cvt_pk_bf16_f32 v218, v240, v241
	v_cvt_pk_bf16_f32 v219, v242, v243
	v_pk_mul_f32 v[90:91], v[90:91], v[244:245] op_sel:[0,1]
	v_pk_mul_f32 v[92:93], v[92:93], v[244:245] op_sel:[0,1]
	v_pk_fma_f32 v[90:91], v[150:151], v[90:91], v[146:147]
	v_pk_fma_f32 v[92:93], v[152:153], v[92:93], v[148:149]
	v_cvt_pk_bf16_f32 v234, v90, v91
	v_cvt_pk_bf16_f32 v235, v92, v93
	v_cndmask_b32_e64 v234, v234, v249, s[0:1]
	v_cndmask_b32_e64 v235, v235, v249, s[0:1]
	v_permlane16_swap_b32_e32 v216, v218
	v_permlane16_swap_b32_e32 v217, v219
	s_nop 1
	v_permlane16_swap_b32_e32 v232, v234
	v_permlane16_swap_b32_e32 v233, v235
	global_store_dwordx4 v247, v[216:219], s[56:57] sc1
	global_store_dwordx4 v247, v[232:235], s[58:59] sc1
	v_cndmask_b32_e32 v240, v86, v248, vcc
	v_cndmask_b32_e32 v241, v87, v248, vcc
	v_cndmask_b32_e32 v242, v88, v248, vcc
	v_cndmask_b32_e32 v243, v89, v248, vcc
	v_cvt_pk_bf16_f32 v220, v240, v241
	v_cvt_pk_bf16_f32 v221, v242, v243
	v_pk_mul_f32 v[86:87], v[86:87], v[244:245] op_sel:[0,1]
	v_pk_mul_f32 v[88:89], v[88:89], v[244:245] op_sel:[0,1]
	v_pk_fma_f32 v[86:87], v[138:139], v[86:87], v[142:143]
	v_pk_fma_f32 v[88:89], v[140:141], v[88:89], v[144:145]
	v_cvt_pk_bf16_f32 v236, v86, v87
	v_cvt_pk_bf16_f32 v237, v88, v89
	v_cndmask_b32_e64 v236, v236, v249, s[0:1]
	v_cndmask_b32_e64 v237, v237, v249, s[0:1]
	v_cndmask_b32_e32 v240, v82, v248, vcc
	v_cndmask_b32_e32 v241, v83, v248, vcc
	v_cndmask_b32_e32 v242, v84, v248, vcc
	v_cndmask_b32_e32 v243, v85, v248, vcc
	v_cvt_pk_bf16_f32 v222, v240, v241
	v_cvt_pk_bf16_f32 v223, v242, v243
	v_pk_mul_f32 v[82:83], v[82:83], v[244:245] op_sel:[0,1]
	v_pk_mul_f32 v[84:85], v[84:85], v[244:245] op_sel:[0,1]
	v_pk_fma_f32 v[82:83], v[130:131], v[82:83], v[134:135]
	v_pk_fma_f32 v[84:85], v[132:133], v[84:85], v[136:137]
	v_cvt_pk_bf16_f32 v238, v82, v83
	v_cvt_pk_bf16_f32 v239, v84, v85
	v_cndmask_b32_e64 v238, v238, v249, s[0:1]
	v_cndmask_b32_e64 v239, v239, v249, s[0:1]
	v_permlane16_swap_b32_e32 v220, v222
	v_permlane16_swap_b32_e32 v221, v223
	s_nop 1
	v_permlane16_swap_b32_e32 v236, v238
	v_permlane16_swap_b32_e32 v237, v239
	global_store_dwordx4 v247, v[220:223], s[56:57] offset:256 sc1
	global_store_dwordx4 v247, v[236:239], s[58:59] offset:256 sc1
	ds_read_b64 v[244:245], v183 offset:8576
	v_add_u32_e32 v247, 0x18000, v246
	s_waitcnt lgkmcnt(0)
	v_cndmask_b32_e32 v240, v78, v248, vcc
	v_cndmask_b32_e32 v241, v79, v248, vcc
	v_cndmask_b32_e32 v242, v80, v248, vcc
	v_cndmask_b32_e32 v243, v81, v248, vcc
	v_cvt_pk_bf16_f32 v216, v240, v241
	v_cvt_pk_bf16_f32 v217, v242, v243
	v_pk_mul_f32 v[78:79], v[78:79], v[244:245] op_sel:[0,1]
	v_pk_mul_f32 v[80:81], v[80:81], v[244:245] op_sel:[0,1]
	v_pk_fma_f32 v[78:79], v[154:155], v[78:79], v[158:159]
	v_pk_fma_f32 v[80:81], v[156:157], v[80:81], v[160:161]
	v_cvt_pk_bf16_f32 v232, v78, v79
	v_cvt_pk_bf16_f32 v233, v80, v81
	v_cndmask_b32_e64 v232, v232, v249, s[0:1]
	v_cndmask_b32_e64 v233, v233, v249, s[0:1]
	v_cndmask_b32_e32 v240, v74, v248, vcc
	v_cndmask_b32_e32 v241, v75, v248, vcc
	v_cndmask_b32_e32 v242, v76, v248, vcc
	v_cndmask_b32_e32 v243, v77, v248, vcc
	v_cvt_pk_bf16_f32 v218, v240, v241
	v_cvt_pk_bf16_f32 v219, v242, v243
	v_pk_mul_f32 v[74:75], v[74:75], v[244:245] op_sel:[0,1]
	v_pk_mul_f32 v[76:77], v[76:77], v[244:245] op_sel:[0,1]
	v_pk_fma_f32 v[74:75], v[150:151], v[74:75], v[146:147]
	v_pk_fma_f32 v[76:77], v[152:153], v[76:77], v[148:149]
	v_cvt_pk_bf16_f32 v234, v74, v75
	v_cvt_pk_bf16_f32 v235, v76, v77
	v_cndmask_b32_e64 v234, v234, v249, s[0:1]
	v_cndmask_b32_e64 v235, v235, v249, s[0:1]
	v_permlane16_swap_b32_e32 v216, v218
	v_permlane16_swap_b32_e32 v217, v219
	s_nop 1
	v_permlane16_swap_b32_e32 v232, v234
	v_permlane16_swap_b32_e32 v233, v235
	global_store_dwordx4 v247, v[216:219], s[56:57] sc1
	global_store_dwordx4 v247, v[232:235], s[58:59] sc1
	v_cndmask_b32_e32 v240, v70, v248, vcc
	v_cndmask_b32_e32 v241, v71, v248, vcc
	v_cndmask_b32_e32 v242, v72, v248, vcc
	v_cndmask_b32_e32 v243, v73, v248, vcc
	v_cvt_pk_bf16_f32 v220, v240, v241
	v_cvt_pk_bf16_f32 v221, v242, v243
	v_pk_mul_f32 v[70:71], v[70:71], v[244:245] op_sel:[0,1]
	v_pk_mul_f32 v[72:73], v[72:73], v[244:245] op_sel:[0,1]
	v_pk_fma_f32 v[70:71], v[138:139], v[70:71], v[142:143]
	v_pk_fma_f32 v[72:73], v[140:141], v[72:73], v[144:145]
	v_cvt_pk_bf16_f32 v236, v70, v71
	v_cvt_pk_bf16_f32 v237, v72, v73
	v_cndmask_b32_e64 v236, v236, v249, s[0:1]
	v_cndmask_b32_e64 v237, v237, v249, s[0:1]
	v_cndmask_b32_e32 v240, v66, v248, vcc
	v_cndmask_b32_e32 v241, v67, v248, vcc
	v_cndmask_b32_e32 v242, v68, v248, vcc
	v_cndmask_b32_e32 v243, v69, v248, vcc
	v_cvt_pk_bf16_f32 v222, v240, v241
	v_cvt_pk_bf16_f32 v223, v242, v243
	v_pk_mul_f32 v[66:67], v[66:67], v[244:245] op_sel:[0,1]
	v_pk_mul_f32 v[68:69], v[68:69], v[244:245] op_sel:[0,1]
	v_pk_fma_f32 v[66:67], v[130:131], v[66:67], v[134:135]
	v_pk_fma_f32 v[68:69], v[132:133], v[68:69], v[136:137]
	v_cvt_pk_bf16_f32 v238, v66, v67
	v_cvt_pk_bf16_f32 v239, v68, v69
	v_cndmask_b32_e64 v238, v238, v249, s[0:1]
	v_cndmask_b32_e64 v239, v239, v249, s[0:1]
	v_permlane16_swap_b32_e32 v220, v222
	v_permlane16_swap_b32_e32 v221, v223
	s_nop 1
	v_permlane16_swap_b32_e32 v236, v238
	v_permlane16_swap_b32_e32 v237, v239
	global_store_dwordx4 v247, v[220:223], s[56:57] offset:256 sc1
	global_store_dwordx4 v247, v[236:239], s[58:59] offset:256 sc1
	ds_read_b64 v[244:245], v183 offset:9216
	v_add_u32_e32 v247, 0x40000, v246
	s_waitcnt lgkmcnt(0)
	v_cndmask_b32_e32 v240, v62, v248, vcc
	v_cndmask_b32_e32 v241, v63, v248, vcc
	v_cndmask_b32_e32 v242, v64, v248, vcc
	v_cndmask_b32_e32 v243, v65, v248, vcc
	v_cvt_pk_bf16_f32 v216, v240, v241
	v_cvt_pk_bf16_f32 v217, v242, v243
	v_pk_mul_f32 v[62:63], v[62:63], v[244:245] op_sel:[0,1]
	v_pk_mul_f32 v[64:65], v[64:65], v[244:245] op_sel:[0,1]
	v_pk_fma_f32 v[62:63], v[154:155], v[62:63], v[158:159]
	v_pk_fma_f32 v[64:65], v[156:157], v[64:65], v[160:161]
	v_cvt_pk_bf16_f32 v232, v62, v63
	v_cvt_pk_bf16_f32 v233, v64, v65
	v_cndmask_b32_e64 v232, v232, v249, s[0:1]
	v_cndmask_b32_e64 v233, v233, v249, s[0:1]
	v_cndmask_b32_e32 v240, v58, v248, vcc
	v_cndmask_b32_e32 v241, v59, v248, vcc
	v_cndmask_b32_e32 v242, v60, v248, vcc
	v_cndmask_b32_e32 v243, v61, v248, vcc
	v_cvt_pk_bf16_f32 v218, v240, v241
	v_cvt_pk_bf16_f32 v219, v242, v243
	v_pk_mul_f32 v[58:59], v[58:59], v[244:245] op_sel:[0,1]
	v_pk_mul_f32 v[60:61], v[60:61], v[244:245] op_sel:[0,1]
	v_pk_fma_f32 v[58:59], v[150:151], v[58:59], v[146:147]
	v_pk_fma_f32 v[60:61], v[152:153], v[60:61], v[148:149]
	v_cvt_pk_bf16_f32 v234, v58, v59
	v_cvt_pk_bf16_f32 v235, v60, v61
	v_cndmask_b32_e64 v234, v234, v249, s[0:1]
	v_cndmask_b32_e64 v235, v235, v249, s[0:1]
	v_permlane16_swap_b32_e32 v216, v218
	v_permlane16_swap_b32_e32 v217, v219
	s_nop 1
	v_permlane16_swap_b32_e32 v232, v234
	v_permlane16_swap_b32_e32 v233, v235
	global_store_dwordx4 v247, v[216:219], s[56:57] sc1
	global_store_dwordx4 v247, v[232:235], s[58:59] sc1
	v_cndmask_b32_e32 v240, v54, v248, vcc
	v_cndmask_b32_e32 v241, v55, v248, vcc
	v_cndmask_b32_e32 v242, v56, v248, vcc
	v_cndmask_b32_e32 v243, v57, v248, vcc
	v_cvt_pk_bf16_f32 v220, v240, v241
	v_cvt_pk_bf16_f32 v221, v242, v243
	v_pk_mul_f32 v[54:55], v[54:55], v[244:245] op_sel:[0,1]
	v_pk_mul_f32 v[56:57], v[56:57], v[244:245] op_sel:[0,1]
	v_pk_fma_f32 v[54:55], v[138:139], v[54:55], v[142:143]
	v_pk_fma_f32 v[56:57], v[140:141], v[56:57], v[144:145]
	v_cvt_pk_bf16_f32 v236, v54, v55
	v_cvt_pk_bf16_f32 v237, v56, v57
	v_cndmask_b32_e64 v236, v236, v249, s[0:1]
	v_cndmask_b32_e64 v237, v237, v249, s[0:1]
	v_cndmask_b32_e32 v240, v50, v248, vcc
	v_cndmask_b32_e32 v241, v51, v248, vcc
	v_cndmask_b32_e32 v242, v52, v248, vcc
	v_cndmask_b32_e32 v243, v53, v248, vcc
	v_cvt_pk_bf16_f32 v222, v240, v241
	v_cvt_pk_bf16_f32 v223, v242, v243
	v_pk_mul_f32 v[50:51], v[50:51], v[244:245] op_sel:[0,1]
	v_pk_mul_f32 v[52:53], v[52:53], v[244:245] op_sel:[0,1]
	v_pk_fma_f32 v[50:51], v[130:131], v[50:51], v[134:135]
	v_pk_fma_f32 v[52:53], v[132:133], v[52:53], v[136:137]
	v_cvt_pk_bf16_f32 v238, v50, v51
	v_cvt_pk_bf16_f32 v239, v52, v53
	v_cndmask_b32_e64 v238, v238, v249, s[0:1]
	v_cndmask_b32_e64 v239, v239, v249, s[0:1]
	v_permlane16_swap_b32_e32 v220, v222
	v_permlane16_swap_b32_e32 v221, v223
	s_nop 1
	v_permlane16_swap_b32_e32 v236, v238
	v_permlane16_swap_b32_e32 v237, v239
	global_store_dwordx4 v247, v[220:223], s[56:57] offset:256 sc1
	global_store_dwordx4 v247, v[236:239], s[58:59] offset:256 sc1
	ds_read_b64 v[244:245], v183 offset:9344
	v_add_u32_e32 v247, 0x48000, v246
	s_waitcnt lgkmcnt(0)
	v_cndmask_b32_e32 v240, v46, v248, vcc
	v_cndmask_b32_e32 v241, v47, v248, vcc
	v_cndmask_b32_e32 v242, v48, v248, vcc
	v_cndmask_b32_e32 v243, v49, v248, vcc
	v_cvt_pk_bf16_f32 v216, v240, v241
	v_cvt_pk_bf16_f32 v217, v242, v243
	v_pk_mul_f32 v[46:47], v[46:47], v[244:245] op_sel:[0,1]
	v_pk_mul_f32 v[48:49], v[48:49], v[244:245] op_sel:[0,1]
	v_pk_fma_f32 v[46:47], v[154:155], v[46:47], v[158:159]
	v_pk_fma_f32 v[48:49], v[156:157], v[48:49], v[160:161]
	v_cvt_pk_bf16_f32 v232, v46, v47
	v_cvt_pk_bf16_f32 v233, v48, v49
	v_cndmask_b32_e64 v232, v232, v249, s[0:1]
	v_cndmask_b32_e64 v233, v233, v249, s[0:1]
	v_cndmask_b32_e32 v240, v42, v248, vcc
	v_cndmask_b32_e32 v241, v43, v248, vcc
	v_cndmask_b32_e32 v242, v44, v248, vcc
	v_cndmask_b32_e32 v243, v45, v248, vcc
	v_cvt_pk_bf16_f32 v218, v240, v241
	v_cvt_pk_bf16_f32 v219, v242, v243
	v_pk_mul_f32 v[42:43], v[42:43], v[244:245] op_sel:[0,1]
	v_pk_mul_f32 v[44:45], v[44:45], v[244:245] op_sel:[0,1]
	v_pk_fma_f32 v[42:43], v[150:151], v[42:43], v[146:147]
	v_pk_fma_f32 v[44:45], v[152:153], v[44:45], v[148:149]
	v_cvt_pk_bf16_f32 v234, v42, v43
	v_cvt_pk_bf16_f32 v235, v44, v45
	v_cndmask_b32_e64 v234, v234, v249, s[0:1]
	v_cndmask_b32_e64 v235, v235, v249, s[0:1]
	v_permlane16_swap_b32_e32 v216, v218
	v_permlane16_swap_b32_e32 v217, v219
	s_nop 1
	v_permlane16_swap_b32_e32 v232, v234
	v_permlane16_swap_b32_e32 v233, v235
	global_store_dwordx4 v247, v[216:219], s[56:57] sc1
	global_store_dwordx4 v247, v[232:235], s[58:59] sc1
	v_cndmask_b32_e32 v240, v38, v248, vcc
	v_cndmask_b32_e32 v241, v39, v248, vcc
	v_cndmask_b32_e32 v242, v40, v248, vcc
	v_cndmask_b32_e32 v243, v41, v248, vcc
	v_cvt_pk_bf16_f32 v220, v240, v241
	v_cvt_pk_bf16_f32 v221, v242, v243
	v_pk_mul_f32 v[38:39], v[38:39], v[244:245] op_sel:[0,1]
	v_pk_mul_f32 v[40:41], v[40:41], v[244:245] op_sel:[0,1]
	v_pk_fma_f32 v[38:39], v[138:139], v[38:39], v[142:143]
	v_pk_fma_f32 v[40:41], v[140:141], v[40:41], v[144:145]
	v_cvt_pk_bf16_f32 v236, v38, v39
	v_cvt_pk_bf16_f32 v237, v40, v41
	v_cndmask_b32_e64 v236, v236, v249, s[0:1]
	v_cndmask_b32_e64 v237, v237, v249, s[0:1]
	v_cndmask_b32_e32 v240, v34, v248, vcc
	v_cndmask_b32_e32 v241, v35, v248, vcc
	v_cndmask_b32_e32 v242, v36, v248, vcc
	v_cndmask_b32_e32 v243, v37, v248, vcc
	v_cvt_pk_bf16_f32 v222, v240, v241
	v_cvt_pk_bf16_f32 v223, v242, v243
	v_pk_mul_f32 v[34:35], v[34:35], v[244:245] op_sel:[0,1]
	v_pk_mul_f32 v[36:37], v[36:37], v[244:245] op_sel:[0,1]
	v_pk_fma_f32 v[34:35], v[130:131], v[34:35], v[134:135]
	v_pk_fma_f32 v[36:37], v[132:133], v[36:37], v[136:137]
	v_cvt_pk_bf16_f32 v238, v34, v35
	v_cvt_pk_bf16_f32 v239, v36, v37
	v_cndmask_b32_e64 v238, v238, v249, s[0:1]
	v_cndmask_b32_e64 v239, v239, v249, s[0:1]
	v_permlane16_swap_b32_e32 v220, v222
	v_permlane16_swap_b32_e32 v221, v223
	s_nop 1
	v_permlane16_swap_b32_e32 v236, v238
	v_permlane16_swap_b32_e32 v237, v239
	global_store_dwordx4 v247, v[220:223], s[56:57] offset:256 sc1
	global_store_dwordx4 v247, v[236:239], s[58:59] offset:256 sc1
	ds_read_b64 v[244:245], v183 offset:9472
	v_add_u32_e32 v247, 0x50000, v246
	s_waitcnt lgkmcnt(0)
	v_cndmask_b32_e32 v240, v30, v248, vcc
	v_cndmask_b32_e32 v241, v31, v248, vcc
	v_cndmask_b32_e32 v242, v32, v248, vcc
	v_cndmask_b32_e32 v243, v33, v248, vcc
	v_cvt_pk_bf16_f32 v216, v240, v241
	v_cvt_pk_bf16_f32 v217, v242, v243
	v_pk_mul_f32 v[30:31], v[30:31], v[244:245] op_sel:[0,1]
	v_pk_mul_f32 v[32:33], v[32:33], v[244:245] op_sel:[0,1]
	v_pk_fma_f32 v[30:31], v[154:155], v[30:31], v[158:159]
	v_pk_fma_f32 v[32:33], v[156:157], v[32:33], v[160:161]
	v_cvt_pk_bf16_f32 v232, v30, v31
	v_cvt_pk_bf16_f32 v233, v32, v33
	v_cndmask_b32_e64 v232, v232, v249, s[0:1]
	v_cndmask_b32_e64 v233, v233, v249, s[0:1]
	v_cndmask_b32_e32 v240, v26, v248, vcc
	v_cndmask_b32_e32 v241, v27, v248, vcc
	v_cndmask_b32_e32 v242, v28, v248, vcc
	v_cndmask_b32_e32 v243, v29, v248, vcc
	v_cvt_pk_bf16_f32 v218, v240, v241
	v_cvt_pk_bf16_f32 v219, v242, v243
	v_pk_mul_f32 v[26:27], v[26:27], v[244:245] op_sel:[0,1]
	v_pk_mul_f32 v[28:29], v[28:29], v[244:245] op_sel:[0,1]
	v_pk_fma_f32 v[26:27], v[150:151], v[26:27], v[146:147]
	v_pk_fma_f32 v[28:29], v[152:153], v[28:29], v[148:149]
	v_cvt_pk_bf16_f32 v234, v26, v27
	v_cvt_pk_bf16_f32 v235, v28, v29
	v_cndmask_b32_e64 v234, v234, v249, s[0:1]
	v_cndmask_b32_e64 v235, v235, v249, s[0:1]
	v_permlane16_swap_b32_e32 v216, v218
	v_permlane16_swap_b32_e32 v217, v219
	s_nop 1
	v_permlane16_swap_b32_e32 v232, v234
	v_permlane16_swap_b32_e32 v233, v235
	global_store_dwordx4 v247, v[216:219], s[56:57] sc1
	global_store_dwordx4 v247, v[232:235], s[58:59] sc1
	v_cndmask_b32_e32 v240, v22, v248, vcc
	v_cndmask_b32_e32 v241, v23, v248, vcc
	v_cndmask_b32_e32 v242, v24, v248, vcc
	v_cndmask_b32_e32 v243, v25, v248, vcc
	v_cvt_pk_bf16_f32 v220, v240, v241
	v_cvt_pk_bf16_f32 v221, v242, v243
	v_pk_mul_f32 v[22:23], v[22:23], v[244:245] op_sel:[0,1]
	v_pk_mul_f32 v[24:25], v[24:25], v[244:245] op_sel:[0,1]
	v_pk_fma_f32 v[22:23], v[138:139], v[22:23], v[142:143]
	v_pk_fma_f32 v[24:25], v[140:141], v[24:25], v[144:145]
	v_cvt_pk_bf16_f32 v236, v22, v23
	v_cvt_pk_bf16_f32 v237, v24, v25
	v_cndmask_b32_e64 v236, v236, v249, s[0:1]
	v_cndmask_b32_e64 v237, v237, v249, s[0:1]
	v_cndmask_b32_e32 v240, v18, v248, vcc
	v_cndmask_b32_e32 v241, v19, v248, vcc
	v_cndmask_b32_e32 v242, v20, v248, vcc
	v_cndmask_b32_e32 v243, v21, v248, vcc
	v_cvt_pk_bf16_f32 v222, v240, v241
	v_cvt_pk_bf16_f32 v223, v242, v243
	v_pk_mul_f32 v[18:19], v[18:19], v[244:245] op_sel:[0,1]
	v_pk_mul_f32 v[20:21], v[20:21], v[244:245] op_sel:[0,1]
	v_pk_fma_f32 v[18:19], v[130:131], v[18:19], v[134:135]
	v_pk_fma_f32 v[20:21], v[132:133], v[20:21], v[136:137]
	v_cvt_pk_bf16_f32 v238, v18, v19
	v_cvt_pk_bf16_f32 v239, v20, v21
	v_cndmask_b32_e64 v238, v238, v249, s[0:1]
	v_cndmask_b32_e64 v239, v239, v249, s[0:1]
	v_permlane16_swap_b32_e32 v220, v222
	v_permlane16_swap_b32_e32 v221, v223
	s_nop 1
	v_permlane16_swap_b32_e32 v236, v238
	v_permlane16_swap_b32_e32 v237, v239
	global_store_dwordx4 v247, v[220:223], s[56:57] offset:256 sc1
	global_store_dwordx4 v247, v[236:239], s[58:59] offset:256 sc1
	ds_read_b64 v[244:245], v183 offset:9600
	v_add_u32_e32 v247, 0x58000, v246
	s_waitcnt lgkmcnt(0)
	v_cndmask_b32_e32 v240, v14, v248, vcc
	v_cndmask_b32_e32 v241, v15, v248, vcc
	v_cndmask_b32_e32 v242, v16, v248, vcc
	v_cndmask_b32_e32 v243, v17, v248, vcc
	v_cvt_pk_bf16_f32 v216, v240, v241
	v_cvt_pk_bf16_f32 v217, v242, v243
	v_pk_mul_f32 v[14:15], v[14:15], v[244:245] op_sel:[0,1]
	v_pk_mul_f32 v[16:17], v[16:17], v[244:245] op_sel:[0,1]
	v_pk_fma_f32 v[14:15], v[154:155], v[14:15], v[158:159]
	v_pk_fma_f32 v[16:17], v[156:157], v[16:17], v[160:161]
	v_cvt_pk_bf16_f32 v232, v14, v15
	v_cvt_pk_bf16_f32 v233, v16, v17
	v_cndmask_b32_e64 v232, v232, v249, s[0:1]
	v_cndmask_b32_e64 v233, v233, v249, s[0:1]
	v_cndmask_b32_e32 v240, v10, v248, vcc
	v_cndmask_b32_e32 v241, v11, v248, vcc
	v_cndmask_b32_e32 v242, v12, v248, vcc
	v_cndmask_b32_e32 v243, v13, v248, vcc
	v_cvt_pk_bf16_f32 v218, v240, v241
	v_cvt_pk_bf16_f32 v219, v242, v243
	v_pk_mul_f32 v[10:11], v[10:11], v[244:245] op_sel:[0,1]
	v_pk_mul_f32 v[12:13], v[12:13], v[244:245] op_sel:[0,1]
	v_pk_fma_f32 v[10:11], v[150:151], v[10:11], v[146:147]
	v_pk_fma_f32 v[12:13], v[152:153], v[12:13], v[148:149]
	v_cvt_pk_bf16_f32 v234, v10, v11
	v_cvt_pk_bf16_f32 v235, v12, v13
	v_cndmask_b32_e64 v234, v234, v249, s[0:1]
	v_cndmask_b32_e64 v235, v235, v249, s[0:1]
	v_permlane16_swap_b32_e32 v216, v218
	v_permlane16_swap_b32_e32 v217, v219
	s_nop 1
	v_permlane16_swap_b32_e32 v232, v234
	v_permlane16_swap_b32_e32 v233, v235
	global_store_dwordx4 v247, v[216:219], s[56:57] sc1
	global_store_dwordx4 v247, v[232:235], s[58:59] sc1
	v_cndmask_b32_e32 v240, v6, v248, vcc
	v_cndmask_b32_e32 v241, v7, v248, vcc
	v_cndmask_b32_e32 v242, v8, v248, vcc
	v_cndmask_b32_e32 v243, v9, v248, vcc
	v_cvt_pk_bf16_f32 v220, v240, v241
	v_cvt_pk_bf16_f32 v221, v242, v243
	v_pk_mul_f32 v[6:7], v[6:7], v[244:245] op_sel:[0,1]
	v_pk_mul_f32 v[8:9], v[8:9], v[244:245] op_sel:[0,1]
	v_pk_fma_f32 v[6:7], v[138:139], v[6:7], v[142:143]
	v_pk_fma_f32 v[8:9], v[140:141], v[8:9], v[144:145]
	v_cvt_pk_bf16_f32 v236, v6, v7
	v_cvt_pk_bf16_f32 v237, v8, v9
	v_cndmask_b32_e64 v236, v236, v249, s[0:1]
	v_cndmask_b32_e64 v237, v237, v249, s[0:1]
	v_cndmask_b32_e32 v240, v2, v248, vcc
	v_cndmask_b32_e32 v241, v3, v248, vcc
	v_cndmask_b32_e32 v242, v4, v248, vcc
	v_cndmask_b32_e32 v243, v5, v248, vcc
	v_cvt_pk_bf16_f32 v222, v240, v241
	v_cvt_pk_bf16_f32 v223, v242, v243
	v_pk_mul_f32 v[2:3], v[2:3], v[244:245] op_sel:[0,1]
	v_pk_mul_f32 v[4:5], v[4:5], v[244:245] op_sel:[0,1]
	v_pk_fma_f32 v[2:3], v[130:131], v[2:3], v[134:135]
	v_pk_fma_f32 v[4:5], v[132:133], v[4:5], v[136:137]
	v_cvt_pk_bf16_f32 v238, v2, v3
	v_cvt_pk_bf16_f32 v239, v4, v5
	v_cndmask_b32_e64 v238, v238, v249, s[0:1]
	v_cndmask_b32_e64 v239, v239, v249, s[0:1]
	v_permlane16_swap_b32_e32 v220, v222
	v_permlane16_swap_b32_e32 v221, v223
	s_nop 1
	v_permlane16_swap_b32_e32 v236, v238
	v_permlane16_swap_b32_e32 v237, v239
	global_store_dwordx4 v247, v[220:223], s[56:57] offset:256 sc1
	global_store_dwordx4 v247, v[236:239], s[58:59] offset:256 sc1
